# GEMM epilogue stores use the global_store form instead of flat_store
# speedup vs baseline: 1.0018x; 1.0018x over previous
.LBB0_241:
	v_lshl_add_u32 v169, s14, 8, v150
	v_lshl_or_b32 v144, s10, 8, v152
	v_mov_b64_e32 v[146:147], s[16:17]
	v_ashrrev_i32_e32 v145, 31, v144
	v_mad_i64_i32 v[146:147], s[10:11], v169, s76, v[146:147]
	v_lshl_add_u64 v[146:147], v[144:145], 1, v[146:147]
	v_cmp_gt_i32_e32 vcc, s77, v144
	s_and_saveexec_b64 s[10:11], vcc
	s_cbranch_execz .LBB0_243
	v_cvt_pk_bf16_f32 v124, v124, v125
	v_cvt_pk_bf16_f32 v125, v126, v127
	v_cvt_pk_bf16_f32 v126, v120, v121
	v_cvt_pk_bf16_f32 v127, v122, v123
	global_store_dwordx4 v[146:147], v[124:127], off
.LBB0_243:
	s_or_b64 exec, exec, s[10:11]
	v_or_b32_e32 v120, 0x80, v144
	v_cmp_gt_i32_e64 s[10:11], s77, v120
	s_and_saveexec_b64 s[14:15], s[10:11]
	s_cbranch_execz .LBB0_245
	v_cvt_pk_bf16_f32 v112, v112, v113
	v_cvt_pk_bf16_f32 v113, v114, v115
	v_cvt_pk_bf16_f32 v114, v104, v105
	v_cvt_pk_bf16_f32 v115, v106, v107
	global_store_dwordx4 v[146:147], v[112:115], off offset:256
.LBB0_245:
	s_or_b64 exec, exec, s[14:15]
	v_or_b32_e32 v106, 16, v169
	v_mov_b64_e32 v[104:105], s[16:17]
	v_mad_i64_i32 v[104:105], s[14:15], v106, s76, v[104:105]
	v_lshl_add_u64 v[104:105], v[144:145], 1, v[104:105]
	s_and_saveexec_b64 s[14:15], vcc
	s_cbranch_execz .LBB0_247
	v_cvt_pk_bf16_f32 v106, v116, v117
	v_cvt_pk_bf16_f32 v107, v118, v119
	v_cvt_pk_bf16_f32 v108, v108, v109
	v_cvt_pk_bf16_f32 v109, v110, v111
	global_store_dwordx4 v[104:105], v[106:109], off
.LBB0_247:
	s_or_b64 exec, exec, s[14:15]
	s_and_saveexec_b64 s[14:15], s[10:11]
	s_cbranch_execz .LBB0_249
	v_cvt_pk_bf16_f32 v96, v96, v97
	v_cvt_pk_bf16_f32 v97, v98, v99
	v_cvt_pk_bf16_f32 v98, v88, v89
	v_cvt_pk_bf16_f32 v99, v90, v91
	global_store_dwordx4 v[104:105], v[96:99], off offset:256
.LBB0_249:
	s_or_b64 exec, exec, s[14:15]
	v_or_b32_e32 v90, 32, v169
	v_mov_b64_e32 v[88:89], s[16:17]
	v_mad_i64_i32 v[88:89], s[14:15], v90, s76, v[88:89]
	v_lshl_add_u64 v[88:89], v[144:145], 1, v[88:89]
	s_and_saveexec_b64 s[14:15], vcc
	s_cbranch_execz .LBB0_251
	v_cvt_pk_bf16_f32 v90, v100, v101
	v_cvt_pk_bf16_f32 v91, v102, v103
	v_cvt_pk_bf16_f32 v92, v92, v93
	v_cvt_pk_bf16_f32 v93, v94, v95
	global_store_dwordx4 v[88:89], v[90:93], off
.LBB0_251:
	s_or_b64 exec, exec, s[14:15]
	s_and_saveexec_b64 s[14:15], s[10:11]
	s_cbranch_execz .LBB0_253
	v_cvt_pk_bf16_f32 v80, v80, v81
	v_cvt_pk_bf16_f32 v81, v82, v83
	v_cvt_pk_bf16_f32 v82, v72, v73
	v_cvt_pk_bf16_f32 v83, v74, v75
	global_store_dwordx4 v[88:89], v[80:83], off offset:256
.LBB0_253:
	s_or_b64 exec, exec, s[14:15]
	v_or_b32_e32 v74, 48, v169
	v_mov_b64_e32 v[72:73], s[16:17]
	v_mad_i64_i32 v[72:73], s[14:15], v74, s76, v[72:73]
	v_lshl_add_u64 v[72:73], v[144:145], 1, v[72:73]
	s_and_saveexec_b64 s[14:15], vcc
	s_cbranch_execz .LBB0_255
	v_cvt_pk_bf16_f32 v74, v84, v85
	v_cvt_pk_bf16_f32 v75, v86, v87
	v_cvt_pk_bf16_f32 v76, v76, v77
	v_cvt_pk_bf16_f32 v77, v78, v79
	global_store_dwordx4 v[72:73], v[74:77], off
.LBB0_255:
	s_or_b64 exec, exec, s[14:15]
	s_and_saveexec_b64 s[14:15], s[10:11]
	s_cbranch_execz .LBB0_257
	v_cvt_pk_bf16_f32 v68, v68, v69
	v_cvt_pk_bf16_f32 v69, v70, v71
	v_cvt_pk_bf16_f32 v70, v64, v65
	v_cvt_pk_bf16_f32 v71, v66, v67
	global_store_dwordx4 v[72:73], v[68:71], off offset:256
.LBB0_257:
	s_or_b64 exec, exec, s[14:15]
	v_add_u32_e32 v66, 0x80, v169
	v_mov_b64_e32 v[64:65], s[16:17]
	v_mad_i64_i32 v[64:65], s[14:15], v66, s76, v[64:65]
	v_lshl_add_u64 v[64:65], v[144:145], 1, v[64:65]
	s_and_saveexec_b64 s[14:15], vcc
	s_cbranch_execz .LBB0_259
	v_cvt_pk_bf16_f32 v60, v60, v61
	v_cvt_pk_bf16_f32 v61, v62, v63
	v_cvt_pk_bf16_f32 v62, v56, v57
	v_cvt_pk_bf16_f32 v63, v58, v59
	global_store_dwordx4 v[64:65], v[60:63], off
.LBB0_259:
	s_or_b64 exec, exec, s[14:15]
	s_and_saveexec_b64 s[14:15], s[10:11]
	s_cbranch_execz .LBB0_261
	v_cvt_pk_bf16_f32 v48, v48, v49
	v_cvt_pk_bf16_f32 v49, v50, v51
	v_cvt_pk_bf16_f32 v50, v40, v41
	v_cvt_pk_bf16_f32 v51, v42, v43
	global_store_dwordx4 v[64:65], v[48:51], off offset:256
.LBB0_261:
	s_or_b64 exec, exec, s[14:15]
	v_add_u32_e32 v42, 0x90, v169
	v_mov_b64_e32 v[40:41], s[16:17]
	v_mad_i64_i32 v[40:41], s[14:15], v42, s76, v[40:41]
	v_lshl_add_u64 v[40:41], v[144:145], 1, v[40:41]
	s_and_saveexec_b64 s[14:15], vcc
	s_cbranch_execz .LBB0_263
	v_cvt_pk_bf16_f32 v42, v52, v53
	v_cvt_pk_bf16_f32 v43, v54, v55
	v_cvt_pk_bf16_f32 v44, v44, v45
	v_cvt_pk_bf16_f32 v45, v46, v47
	global_store_dwordx4 v[40:41], v[42:45], off
.LBB0_263:
	s_or_b64 exec, exec, s[14:15]
	s_and_saveexec_b64 s[14:15], s[10:11]
	s_cbranch_execz .LBB0_265
	v_cvt_pk_bf16_f32 v32, v32, v33
	v_cvt_pk_bf16_f32 v33, v34, v35
	v_cvt_pk_bf16_f32 v34, v24, v25
	v_cvt_pk_bf16_f32 v35, v26, v27
	global_store_dwordx4 v[40:41], v[32:35], off offset:256
.LBB0_265:
	s_or_b64 exec, exec, s[14:15]
	v_add_u32_e32 v26, 0xa0, v169
	v_mov_b64_e32 v[24:25], s[16:17]
	v_mad_i64_i32 v[24:25], s[14:15], v26, s76, v[24:25]
	v_lshl_add_u64 v[24:25], v[144:145], 1, v[24:25]
	s_and_saveexec_b64 s[14:15], vcc
	s_cbranch_execz .LBB0_267
	v_cvt_pk_bf16_f32 v26, v36, v37
	v_cvt_pk_bf16_f32 v27, v38, v39
	v_cvt_pk_bf16_f32 v28, v28, v29
	v_cvt_pk_bf16_f32 v29, v30, v31
	global_store_dwordx4 v[24:25], v[26:29], off
.LBB0_267:
	s_or_b64 exec, exec, s[14:15]
	s_and_saveexec_b64 s[14:15], s[10:11]
	s_cbranch_execz .LBB0_269
	v_cvt_pk_bf16_f32 v16, v16, v17
	v_cvt_pk_bf16_f32 v17, v18, v19
	v_cvt_pk_bf16_f32 v18, v8, v9
	v_cvt_pk_bf16_f32 v19, v10, v11
	global_store_dwordx4 v[24:25], v[16:19], off offset:256
.LBB0_269:
	s_or_b64 exec, exec, s[14:15]
	v_add_u32_e32 v10, 0xb0, v169
	v_mov_b64_e32 v[8:9], s[16:17]
	v_mad_i64_i32 v[8:9], s[14:15], v10, s76, v[8:9]
	v_lshl_add_u64 v[8:9], v[144:145], 1, v[8:9]
	s_and_saveexec_b64 s[14:15], vcc
	s_cbranch_execz .LBB0_271
	v_cvt_pk_bf16_f32 v10, v20, v21
	v_cvt_pk_bf16_f32 v11, v22, v23
	v_cvt_pk_bf16_f32 v12, v12, v13
	v_cvt_pk_bf16_f32 v13, v14, v15
	global_store_dwordx4 v[8:9], v[10:13], off
.LBB0_271:
	s_or_b64 exec, exec, s[14:15]
	s_and_saveexec_b64 s[14:15], s[10:11]
	s_cbranch_execz .LBB0_217
	v_cvt_pk_bf16_f32 v4, v4, v5
	v_cvt_pk_bf16_f32 v5, v6, v7
	v_cvt_pk_bf16_f32 v6, v0, v1
	v_cvt_pk_bf16_f32 v7, v2, v3
	global_store_dwordx4 v[8:9], v[4:7], off offset:256
	s_branch .LBB0_217

.LBB0_1478:
	v_lshl_add_u32 v146, s20, 8, v152
	v_ashrrev_i32_e32 v147, 31, v146
	v_lshl_or_b32 v144, s10, 8, v154
	v_lshlrev_b64 v[148:149], 11, v[146:147]
	v_ashrrev_i32_e32 v145, 31, v144
	v_lshl_add_u64 v[148:149], s[22:23], 0, v[148:149]
	v_lshl_add_u64 v[148:149], v[144:145], 1, v[148:149]
	v_cmp_gt_i32_e32 vcc, s71, v144
	s_and_saveexec_b64 s[10:11], vcc
	s_cbranch_execz .LBB0_1480
	v_cvt_pk_bf16_f32 v124, v124, v125
	v_cvt_pk_bf16_f32 v125, v126, v127
	v_cvt_pk_bf16_f32 v126, v120, v121
	v_cvt_pk_bf16_f32 v127, v122, v123
	global_store_dwordx4 v[148:149], v[124:127], off
.LBB0_1480:
	s_or_b64 exec, exec, s[10:11]
	v_or_b32_e32 v120, 0x80, v144
	v_cmp_gt_i32_e64 s[10:11], s71, v120
	s_and_saveexec_b64 s[20:21], s[10:11]
	s_cbranch_execz .LBB0_1482
	v_cvt_pk_bf16_f32 v112, v112, v113
	v_cvt_pk_bf16_f32 v113, v114, v115
	v_cvt_pk_bf16_f32 v114, v104, v105
	v_cvt_pk_bf16_f32 v115, v106, v107
	global_store_dwordx4 v[148:149], v[112:115], off offset:256
.LBB0_1482:
	s_or_b64 exec, exec, s[20:21]
	v_or_b32_e32 v104, 16, v146
	v_ashrrev_i32_e32 v105, 31, v104
	v_lshlrev_b64 v[104:105], 11, v[104:105]
	v_lshl_add_u64 v[104:105], s[22:23], 0, v[104:105]
	v_lshl_add_u64 v[104:105], v[144:145], 1, v[104:105]
	s_and_saveexec_b64 s[20:21], vcc
	s_cbranch_execz .LBB0_1484
	v_cvt_pk_bf16_f32 v106, v116, v117
	v_cvt_pk_bf16_f32 v107, v118, v119
	v_cvt_pk_bf16_f32 v108, v108, v109
	v_cvt_pk_bf16_f32 v109, v110, v111
	global_store_dwordx4 v[104:105], v[106:109], off
.LBB0_1484:
	s_or_b64 exec, exec, s[20:21]
	s_and_saveexec_b64 s[20:21], s[10:11]
	s_cbranch_execz .LBB0_1486
	v_cvt_pk_bf16_f32 v96, v96, v97
	v_cvt_pk_bf16_f32 v97, v98, v99
	v_cvt_pk_bf16_f32 v98, v88, v89
	v_cvt_pk_bf16_f32 v99, v90, v91
	global_store_dwordx4 v[104:105], v[96:99], off offset:256
.LBB0_1486:
	s_or_b64 exec, exec, s[20:21]
	v_or_b32_e32 v88, 32, v146
	v_ashrrev_i32_e32 v89, 31, v88
	v_lshlrev_b64 v[88:89], 11, v[88:89]
	v_lshl_add_u64 v[88:89], s[22:23], 0, v[88:89]
	v_lshl_add_u64 v[88:89], v[144:145], 1, v[88:89]
	s_and_saveexec_b64 s[20:21], vcc
	s_cbranch_execz .LBB0_1488
	v_cvt_pk_bf16_f32 v90, v100, v101
	v_cvt_pk_bf16_f32 v91, v102, v103
	v_cvt_pk_bf16_f32 v92, v92, v93
	v_cvt_pk_bf16_f32 v93, v94, v95
	global_store_dwordx4 v[88:89], v[90:93], off
.LBB0_1488:
	s_or_b64 exec, exec, s[20:21]
	s_and_saveexec_b64 s[20:21], s[10:11]
	s_cbranch_execz .LBB0_1490
	v_cvt_pk_bf16_f32 v80, v80, v81
	v_cvt_pk_bf16_f32 v81, v82, v83
	v_cvt_pk_bf16_f32 v82, v72, v73
	v_cvt_pk_bf16_f32 v83, v74, v75
	global_store_dwordx4 v[88:89], v[80:83], off offset:256
.LBB0_1490:
	s_or_b64 exec, exec, s[20:21]
	v_or_b32_e32 v72, 48, v146
	v_ashrrev_i32_e32 v73, 31, v72
	v_lshlrev_b64 v[72:73], 11, v[72:73]
	v_lshl_add_u64 v[72:73], s[22:23], 0, v[72:73]
	v_lshl_add_u64 v[72:73], v[144:145], 1, v[72:73]
	s_and_saveexec_b64 s[20:21], vcc
	s_cbranch_execz .LBB0_1492
	v_cvt_pk_bf16_f32 v74, v84, v85
	v_cvt_pk_bf16_f32 v75, v86, v87
	v_cvt_pk_bf16_f32 v76, v76, v77
	v_cvt_pk_bf16_f32 v77, v78, v79
	global_store_dwordx4 v[72:73], v[74:77], off
.LBB0_1492:
	s_or_b64 exec, exec, s[20:21]
	s_and_saveexec_b64 s[20:21], s[10:11]
	s_cbranch_execz .LBB0_1494
	v_cvt_pk_bf16_f32 v68, v68, v69
	v_cvt_pk_bf16_f32 v69, v70, v71
	v_cvt_pk_bf16_f32 v70, v64, v65
	v_cvt_pk_bf16_f32 v71, v66, v67
	global_store_dwordx4 v[72:73], v[68:71], off offset:256
.LBB0_1494:
	s_or_b64 exec, exec, s[20:21]
	v_lshlrev_b64 v[64:65], 11, v[146:147]
	v_lshl_add_u64 v[64:65], s[22:23], 0, v[64:65]
	v_lshl_add_u64 v[64:65], v[144:145], 1, v[64:65]
	s_mov_b64 s[20:21], 0x40000
	v_lshl_add_u64 v[64:65], v[64:65], 0, s[20:21]
	s_and_saveexec_b64 s[20:21], vcc
	s_cbranch_execz .LBB0_1496
	v_cvt_pk_bf16_f32 v60, v60, v61
	v_cvt_pk_bf16_f32 v61, v62, v63
	v_cvt_pk_bf16_f32 v62, v56, v57
	v_cvt_pk_bf16_f32 v63, v58, v59
	global_store_dwordx4 v[64:65], v[60:63], off
.LBB0_1496:
	s_or_b64 exec, exec, s[20:21]
	s_and_saveexec_b64 s[20:21], s[10:11]
	s_cbranch_execz .LBB0_1498
	v_cvt_pk_bf16_f32 v48, v48, v49
	v_cvt_pk_bf16_f32 v49, v50, v51
	v_cvt_pk_bf16_f32 v50, v40, v41
	v_cvt_pk_bf16_f32 v51, v42, v43
	global_store_dwordx4 v[64:65], v[48:51], off offset:256
.LBB0_1498:
	s_or_b64 exec, exec, s[20:21]
	v_lshlrev_b64 v[40:41], 11, v[146:147]
	v_lshl_add_u64 v[40:41], s[22:23], 0, v[40:41]
	v_lshl_add_u64 v[40:41], v[144:145], 1, v[40:41]
	s_mov_b64 s[20:21], 0x48000
	v_lshl_add_u64 v[40:41], v[40:41], 0, s[20:21]
	s_and_saveexec_b64 s[20:21], vcc
	s_cbranch_execz .LBB0_1500
	v_cvt_pk_bf16_f32 v42, v52, v53
	v_cvt_pk_bf16_f32 v43, v54, v55
	v_cvt_pk_bf16_f32 v44, v44, v45
	v_cvt_pk_bf16_f32 v45, v46, v47
	global_store_dwordx4 v[40:41], v[42:45], off
.LBB0_1500:
	s_or_b64 exec, exec, s[20:21]
	s_and_saveexec_b64 s[20:21], s[10:11]
	s_cbranch_execz .LBB0_1502
	v_cvt_pk_bf16_f32 v32, v32, v33
	v_cvt_pk_bf16_f32 v33, v34, v35
	v_cvt_pk_bf16_f32 v34, v24, v25
	v_cvt_pk_bf16_f32 v35, v26, v27
	global_store_dwordx4 v[40:41], v[32:35], off offset:256
.LBB0_1502:
	s_or_b64 exec, exec, s[20:21]
	v_lshlrev_b64 v[24:25], 11, v[146:147]
	v_lshl_add_u64 v[24:25], s[22:23], 0, v[24:25]
	v_lshl_add_u64 v[24:25], v[144:145], 1, v[24:25]
	s_mov_b64 s[20:21], 0x50000
	v_lshl_add_u64 v[24:25], v[24:25], 0, s[20:21]
	s_and_saveexec_b64 s[20:21], vcc
	s_cbranch_execz .LBB0_1504
	v_cvt_pk_bf16_f32 v26, v36, v37
	v_cvt_pk_bf16_f32 v27, v38, v39
	v_cvt_pk_bf16_f32 v28, v28, v29
	v_cvt_pk_bf16_f32 v29, v30, v31
	global_store_dwordx4 v[24:25], v[26:29], off
.LBB0_1504:
	s_or_b64 exec, exec, s[20:21]
	s_and_saveexec_b64 s[20:21], s[10:11]
	s_cbranch_execz .LBB0_1506
	v_cvt_pk_bf16_f32 v16, v16, v17
	v_cvt_pk_bf16_f32 v17, v18, v19
	v_cvt_pk_bf16_f32 v18, v8, v9
	v_cvt_pk_bf16_f32 v19, v10, v11
	global_store_dwordx4 v[24:25], v[16:19], off offset:256
.LBB0_1506:
	s_or_b64 exec, exec, s[20:21]
	v_lshlrev_b64 v[8:9], 11, v[146:147]
	v_lshl_add_u64 v[8:9], s[22:23], 0, v[8:9]
	v_lshl_add_u64 v[8:9], v[144:145], 1, v[8:9]
	v_lshl_add_u64 v[8:9], v[8:9], 0, s[28:29]
	s_and_saveexec_b64 s[20:21], vcc
	s_cbranch_execz .LBB0_1508
	v_cvt_pk_bf16_f32 v10, v20, v21
	v_cvt_pk_bf16_f32 v11, v22, v23
	v_cvt_pk_bf16_f32 v12, v12, v13
	v_cvt_pk_bf16_f32 v13, v14, v15
	global_store_dwordx4 v[8:9], v[10:13], off
.LBB0_1508:
	s_or_b64 exec, exec, s[20:21]
	s_and_saveexec_b64 s[20:21], s[10:11]
	s_cbranch_execz .LBB0_1454
	v_cvt_pk_bf16_f32 v4, v4, v5
	v_cvt_pk_bf16_f32 v5, v6, v7
	v_cvt_pk_bf16_f32 v6, v0, v1
	v_cvt_pk_bf16_f32 v7, v2, v3
	global_store_dwordx4 v[8:9], v[4:7], off offset:256
	s_branch .LBB0_1454

.LBB0_1749:
	v_lshl_add_u32 v146, s44, 8, v151
	v_ashrrev_i32_e32 v147, 31, v146
	v_lshl_or_b32 v144, s42, 8, v153
	v_lshlrev_b64 v[148:149], 13, v[146:147]
	v_ashrrev_i32_e32 v145, 31, v144
	v_lshl_add_u64 v[148:149], s[14:15], 0, v[148:149]
	v_lshl_add_u64 v[148:149], v[144:145], 1, v[148:149]
	v_cmp_gt_i32_e32 vcc, s81, v144
	s_and_saveexec_b64 s[10:11], vcc
	s_cbranch_execz .LBB0_1751
	v_max_f32_e32 v124, 0, v124
	v_max_f32_e32 v125, 0, v125
	v_max_f32_e32 v126, 0, v126
	v_max_f32_e32 v127, 0, v127
	v_max_f32_e32 v120, 0, v120
	v_max_f32_e32 v121, 0, v121
	v_max_f32_e32 v122, 0, v122
	v_max_f32_e32 v123, 0, v123
	v_pk_mul_f32 v[124:125], v[124:125], v[124:125]
	v_pk_mul_f32 v[126:127], v[126:127], v[126:127]
	v_pk_mul_f32 v[120:121], v[120:121], v[120:121]
	v_pk_mul_f32 v[122:123], v[122:123], v[122:123]
	v_cvt_pk_bf16_f32 v120, v120, v121
	v_cvt_pk_bf16_f32 v121, v122, v123
	v_cvt_pk_bf16_f32 v122, v124, v125
	v_cvt_pk_bf16_f32 v123, v126, v127
	global_store_dwordx4 v[148:149], v[120:123], off
.LBB0_1751:
	s_or_b64 exec, exec, s[10:11]
	s_nop 0
	v_or_b32_e32 v120, 0x80, v144
	v_cmp_gt_i32_e64 s[10:11], s81, v120
	s_and_saveexec_b64 s[42:43], s[10:11]
	s_load_dwordx2 s[84:85], s[90:91], 0x120
	s_cbranch_execz .LBB0_1753
	v_max_f32_e32 v116, 0, v116
	v_max_f32_e32 v117, 0, v117
	v_max_f32_e32 v118, 0, v118
	v_max_f32_e32 v119, 0, v119
	v_max_f32_e32 v112, 0, v112
	v_max_f32_e32 v113, 0, v113
	v_max_f32_e32 v114, 0, v114
	v_max_f32_e32 v115, 0, v115
	v_pk_mul_f32 v[116:117], v[116:117], v[116:117]
	v_pk_mul_f32 v[118:119], v[118:119], v[118:119]
	v_pk_mul_f32 v[112:113], v[112:113], v[112:113]
	v_pk_mul_f32 v[114:115], v[114:115], v[114:115]
	v_cvt_pk_bf16_f32 v112, v112, v113
	v_cvt_pk_bf16_f32 v113, v114, v115
	v_cvt_pk_bf16_f32 v114, v116, v117
	v_cvt_pk_bf16_f32 v115, v118, v119
	global_store_dwordx4 v[148:149], v[112:115], off offset:256
.LBB0_1753:
	s_or_b64 exec, exec, s[42:43]
	s_nop 0
	v_or_b32_e32 v112, 16, v146
	v_ashrrev_i32_e32 v113, 31, v112
	v_lshlrev_b64 v[112:113], 13, v[112:113]
	v_lshl_add_u64 v[112:113], s[14:15], 0, v[112:113]
	v_lshl_add_u64 v[112:113], v[144:145], 1, v[112:113]
	s_and_saveexec_b64 s[42:43], vcc
	s_cbranch_execz .LBB0_1755
	v_max_f32_e32 v108, 0, v108
	v_max_f32_e32 v109, 0, v109
	v_max_f32_e32 v110, 0, v110
	v_max_f32_e32 v111, 0, v111
	v_max_f32_e32 v104, 0, v104
	v_max_f32_e32 v105, 0, v105
	v_max_f32_e32 v106, 0, v106
	v_max_f32_e32 v107, 0, v107
	v_pk_mul_f32 v[108:109], v[108:109], v[108:109]
	v_pk_mul_f32 v[110:111], v[110:111], v[110:111]
	v_pk_mul_f32 v[104:105], v[104:105], v[104:105]
	v_pk_mul_f32 v[106:107], v[106:107], v[106:107]
	v_cvt_pk_bf16_f32 v104, v104, v105
	v_cvt_pk_bf16_f32 v105, v106, v107
	v_cvt_pk_bf16_f32 v106, v108, v109
	v_cvt_pk_bf16_f32 v107, v110, v111
	global_store_dwordx4 v[112:113], v[104:107], off
.LBB0_1755:
	s_or_b64 exec, exec, s[42:43]
	s_and_saveexec_b64 s[42:43], s[10:11]
	s_cbranch_execz .LBB0_1757
	v_max_f32_e32 v100, 0, v100
	v_max_f32_e32 v101, 0, v101
	v_max_f32_e32 v102, 0, v102
	v_max_f32_e32 v103, 0, v103
	v_max_f32_e32 v96, 0, v96
	v_max_f32_e32 v97, 0, v97
	v_max_f32_e32 v98, 0, v98
	v_max_f32_e32 v99, 0, v99
	v_pk_mul_f32 v[100:101], v[100:101], v[100:101]
	v_pk_mul_f32 v[102:103], v[102:103], v[102:103]
	v_pk_mul_f32 v[96:97], v[96:97], v[96:97]
	v_pk_mul_f32 v[98:99], v[98:99], v[98:99]
	v_cvt_pk_bf16_f32 v96, v96, v97
	v_cvt_pk_bf16_f32 v97, v98, v99
	v_cvt_pk_bf16_f32 v98, v100, v101
	v_cvt_pk_bf16_f32 v99, v102, v103
	global_store_dwordx4 v[112:113], v[96:99], off offset:256
.LBB0_1757:
	s_or_b64 exec, exec, s[42:43]
	s_nop 0
	v_or_b32_e32 v96, 32, v146
	v_ashrrev_i32_e32 v97, 31, v96
	v_lshlrev_b64 v[96:97], 13, v[96:97]
	v_lshl_add_u64 v[96:97], s[14:15], 0, v[96:97]
	v_lshl_add_u64 v[96:97], v[144:145], 1, v[96:97]
	s_and_saveexec_b64 s[42:43], vcc
	s_cbranch_execz .LBB0_1759
	v_max_f32_e32 v92, 0, v92
	v_max_f32_e32 v93, 0, v93
	v_max_f32_e32 v94, 0, v94
	v_max_f32_e32 v95, 0, v95
	v_max_f32_e32 v88, 0, v88
	v_max_f32_e32 v89, 0, v89
	v_max_f32_e32 v90, 0, v90
	v_max_f32_e32 v91, 0, v91
	v_pk_mul_f32 v[92:93], v[92:93], v[92:93]
	v_pk_mul_f32 v[94:95], v[94:95], v[94:95]
	v_pk_mul_f32 v[88:89], v[88:89], v[88:89]
	v_pk_mul_f32 v[90:91], v[90:91], v[90:91]
	v_cvt_pk_bf16_f32 v88, v88, v89
	v_cvt_pk_bf16_f32 v89, v90, v91
	v_cvt_pk_bf16_f32 v90, v92, v93
	v_cvt_pk_bf16_f32 v91, v94, v95
	global_store_dwordx4 v[96:97], v[88:91], off
.LBB0_1759:
	s_or_b64 exec, exec, s[42:43]
	s_and_saveexec_b64 s[42:43], s[10:11]
	s_cbranch_execz .LBB0_1761
	v_max_f32_e32 v84, 0, v84
	v_max_f32_e32 v85, 0, v85
	v_max_f32_e32 v86, 0, v86
	v_max_f32_e32 v87, 0, v87
	v_max_f32_e32 v80, 0, v80
	v_max_f32_e32 v81, 0, v81
	v_max_f32_e32 v82, 0, v82
	v_max_f32_e32 v83, 0, v83
	v_pk_mul_f32 v[84:85], v[84:85], v[84:85]
	v_pk_mul_f32 v[86:87], v[86:87], v[86:87]
	v_pk_mul_f32 v[80:81], v[80:81], v[80:81]
	v_pk_mul_f32 v[82:83], v[82:83], v[82:83]
	v_cvt_pk_bf16_f32 v80, v80, v81
	v_cvt_pk_bf16_f32 v81, v82, v83
	v_cvt_pk_bf16_f32 v82, v84, v85
	v_cvt_pk_bf16_f32 v83, v86, v87
	global_store_dwordx4 v[96:97], v[80:83], off offset:256
.LBB0_1761:
	s_or_b64 exec, exec, s[42:43]
	s_nop 0
	v_or_b32_e32 v80, 48, v146
	v_ashrrev_i32_e32 v81, 31, v80
	v_lshlrev_b64 v[80:81], 13, v[80:81]
	v_lshl_add_u64 v[80:81], s[14:15], 0, v[80:81]
	v_lshl_add_u64 v[80:81], v[144:145], 1, v[80:81]
	s_and_saveexec_b64 s[42:43], vcc
	s_cbranch_execz .LBB0_1763
	v_max_f32_e32 v76, 0, v76
	v_max_f32_e32 v77, 0, v77
	v_max_f32_e32 v78, 0, v78
	v_max_f32_e32 v79, 0, v79
	v_max_f32_e32 v72, 0, v72
	v_max_f32_e32 v73, 0, v73
	v_max_f32_e32 v74, 0, v74
	v_max_f32_e32 v75, 0, v75
	v_pk_mul_f32 v[76:77], v[76:77], v[76:77]
	v_pk_mul_f32 v[78:79], v[78:79], v[78:79]
	v_pk_mul_f32 v[72:73], v[72:73], v[72:73]
	v_pk_mul_f32 v[74:75], v[74:75], v[74:75]
	v_cvt_pk_bf16_f32 v72, v72, v73
	v_cvt_pk_bf16_f32 v73, v74, v75
	v_cvt_pk_bf16_f32 v74, v76, v77
	v_cvt_pk_bf16_f32 v75, v78, v79
	global_store_dwordx4 v[80:81], v[72:75], off
.LBB0_1763:
	s_or_b64 exec, exec, s[42:43]
	s_and_saveexec_b64 s[42:43], s[10:11]
	s_cbranch_execz .LBB0_1765
	v_max_f32_e32 v68, 0, v68
	v_max_f32_e32 v69, 0, v69
	v_max_f32_e32 v70, 0, v70
	v_max_f32_e32 v71, 0, v71
	v_max_f32_e32 v64, 0, v64
	v_max_f32_e32 v65, 0, v65
	v_max_f32_e32 v66, 0, v66
	v_max_f32_e32 v67, 0, v67
	v_pk_mul_f32 v[68:69], v[68:69], v[68:69]
	v_pk_mul_f32 v[70:71], v[70:71], v[70:71]
	v_pk_mul_f32 v[64:65], v[64:65], v[64:65]
	v_pk_mul_f32 v[66:67], v[66:67], v[66:67]
	v_cvt_pk_bf16_f32 v64, v64, v65
	v_cvt_pk_bf16_f32 v65, v66, v67
	v_cvt_pk_bf16_f32 v66, v68, v69
	v_cvt_pk_bf16_f32 v67, v70, v71
	global_store_dwordx4 v[80:81], v[64:67], off offset:256
.LBB0_1765:
	s_or_b64 exec, exec, s[42:43]
	s_nop 0
	v_lshlrev_b64 v[64:65], 13, v[146:147]
	v_lshl_add_u64 v[64:65], s[14:15], 0, v[64:65]
	v_lshl_add_u64 v[64:65], v[144:145], 1, v[64:65]
	v_lshl_add_u64 v[64:65], v[64:65], 0, s[22:23]
	s_and_saveexec_b64 s[42:43], vcc
	s_cbranch_execz .LBB0_1767
	v_max_f32_e32 v60, 0, v60
	v_max_f32_e32 v61, 0, v61
	v_max_f32_e32 v62, 0, v62
	v_max_f32_e32 v63, 0, v63
	v_max_f32_e32 v56, 0, v56
	v_max_f32_e32 v57, 0, v57
	v_max_f32_e32 v58, 0, v58
	v_max_f32_e32 v59, 0, v59
	v_pk_mul_f32 v[60:61], v[60:61], v[60:61]
	v_pk_mul_f32 v[62:63], v[62:63], v[62:63]
	v_pk_mul_f32 v[56:57], v[56:57], v[56:57]
	v_pk_mul_f32 v[58:59], v[58:59], v[58:59]
	v_cvt_pk_bf16_f32 v56, v56, v57
	v_cvt_pk_bf16_f32 v57, v58, v59
	v_cvt_pk_bf16_f32 v58, v60, v61
	v_cvt_pk_bf16_f32 v59, v62, v63
	global_store_dwordx4 v[64:65], v[56:59], off
.LBB0_1767:
	s_or_b64 exec, exec, s[42:43]
	s_and_saveexec_b64 s[42:43], s[10:11]
	s_cbranch_execz .LBB0_1769
	v_max_f32_e32 v52, 0, v52
	v_max_f32_e32 v53, 0, v53
	v_max_f32_e32 v54, 0, v54
	v_max_f32_e32 v55, 0, v55
	v_max_f32_e32 v48, 0, v48
	v_max_f32_e32 v49, 0, v49
	v_max_f32_e32 v50, 0, v50
	v_max_f32_e32 v51, 0, v51
	v_pk_mul_f32 v[52:53], v[52:53], v[52:53]
	v_pk_mul_f32 v[54:55], v[54:55], v[54:55]
	v_pk_mul_f32 v[48:49], v[48:49], v[48:49]
	v_pk_mul_f32 v[50:51], v[50:51], v[50:51]
	v_cvt_pk_bf16_f32 v48, v48, v49
	v_cvt_pk_bf16_f32 v49, v50, v51
	v_cvt_pk_bf16_f32 v50, v52, v53
	v_cvt_pk_bf16_f32 v51, v54, v55
	global_store_dwordx4 v[64:65], v[48:51], off offset:256
.LBB0_1769:
	s_or_b64 exec, exec, s[42:43]
	s_nop 0
	v_lshlrev_b64 v[48:49], 13, v[146:147]
	v_lshl_add_u64 v[48:49], s[14:15], 0, v[48:49]
	v_lshl_add_u64 v[48:49], v[144:145], 1, v[48:49]
	v_lshl_add_u64 v[48:49], v[48:49], 0, s[24:25]
	s_and_saveexec_b64 s[42:43], vcc
	s_cbranch_execz .LBB0_1771
	v_max_f32_e32 v44, 0, v44
	v_max_f32_e32 v45, 0, v45
	v_max_f32_e32 v46, 0, v46
	v_max_f32_e32 v47, 0, v47
	v_max_f32_e32 v40, 0, v40
	v_max_f32_e32 v41, 0, v41
	v_max_f32_e32 v42, 0, v42
	v_max_f32_e32 v43, 0, v43
	v_pk_mul_f32 v[44:45], v[44:45], v[44:45]
	v_pk_mul_f32 v[46:47], v[46:47], v[46:47]
	v_pk_mul_f32 v[40:41], v[40:41], v[40:41]
	v_pk_mul_f32 v[42:43], v[42:43], v[42:43]
	v_cvt_pk_bf16_f32 v40, v40, v41
	v_cvt_pk_bf16_f32 v41, v42, v43
	v_cvt_pk_bf16_f32 v42, v44, v45
	v_cvt_pk_bf16_f32 v43, v46, v47
	global_store_dwordx4 v[48:49], v[40:43], off
.LBB0_1771:
	s_or_b64 exec, exec, s[42:43]
	s_and_saveexec_b64 s[42:43], s[10:11]
	s_cbranch_execz .LBB0_1773
	v_max_f32_e32 v36, 0, v36
	v_max_f32_e32 v37, 0, v37
	v_max_f32_e32 v38, 0, v38
	v_max_f32_e32 v39, 0, v39
	v_max_f32_e32 v32, 0, v32
	v_max_f32_e32 v33, 0, v33
	v_max_f32_e32 v34, 0, v34
	v_max_f32_e32 v35, 0, v35
	v_pk_mul_f32 v[36:37], v[36:37], v[36:37]
	v_pk_mul_f32 v[38:39], v[38:39], v[38:39]
	v_pk_mul_f32 v[32:33], v[32:33], v[32:33]
	v_pk_mul_f32 v[34:35], v[34:35], v[34:35]
	v_cvt_pk_bf16_f32 v32, v32, v33
	v_cvt_pk_bf16_f32 v33, v34, v35
	v_cvt_pk_bf16_f32 v34, v36, v37
	v_cvt_pk_bf16_f32 v35, v38, v39
	global_store_dwordx4 v[48:49], v[32:35], off offset:256
.LBB0_1773:
	s_or_b64 exec, exec, s[42:43]
	s_nop 0
	v_lshlrev_b64 v[32:33], 13, v[146:147]
	v_lshl_add_u64 v[32:33], s[14:15], 0, v[32:33]
	v_lshl_add_u64 v[32:33], v[144:145], 1, v[32:33]
	v_lshl_add_u64 v[32:33], v[32:33], 0, s[26:27]
	s_and_saveexec_b64 s[42:43], vcc
	s_cbranch_execz .LBB0_1775
	v_max_f32_e32 v28, 0, v28
	v_max_f32_e32 v29, 0, v29
	v_max_f32_e32 v30, 0, v30
	v_max_f32_e32 v31, 0, v31
	v_max_f32_e32 v24, 0, v24
	v_max_f32_e32 v25, 0, v25
	v_max_f32_e32 v26, 0, v26
	v_max_f32_e32 v27, 0, v27
	v_pk_mul_f32 v[28:29], v[28:29], v[28:29]
	v_pk_mul_f32 v[30:31], v[30:31], v[30:31]
	v_pk_mul_f32 v[24:25], v[24:25], v[24:25]
	v_pk_mul_f32 v[26:27], v[26:27], v[26:27]
	v_cvt_pk_bf16_f32 v24, v24, v25
	v_cvt_pk_bf16_f32 v25, v26, v27
	v_cvt_pk_bf16_f32 v26, v28, v29
	v_cvt_pk_bf16_f32 v27, v30, v31
	global_store_dwordx4 v[32:33], v[24:27], off
.LBB0_1775:
	s_or_b64 exec, exec, s[42:43]
	s_and_saveexec_b64 s[42:43], s[10:11]
	s_cbranch_execz .LBB0_1777
	v_max_f32_e32 v20, 0, v20
	v_max_f32_e32 v21, 0, v21
	v_max_f32_e32 v22, 0, v22
	v_max_f32_e32 v23, 0, v23
	v_max_f32_e32 v16, 0, v16
	v_max_f32_e32 v17, 0, v17
	v_max_f32_e32 v18, 0, v18
	v_max_f32_e32 v19, 0, v19
	v_pk_mul_f32 v[20:21], v[20:21], v[20:21]
	v_pk_mul_f32 v[22:23], v[22:23], v[22:23]
	v_pk_mul_f32 v[16:17], v[16:17], v[16:17]
	v_pk_mul_f32 v[18:19], v[18:19], v[18:19]
	v_cvt_pk_bf16_f32 v16, v16, v17
	v_cvt_pk_bf16_f32 v17, v18, v19
	v_cvt_pk_bf16_f32 v18, v20, v21
	v_cvt_pk_bf16_f32 v19, v22, v23
	global_store_dwordx4 v[32:33], v[16:19], off offset:256
.LBB0_1777:
	s_or_b64 exec, exec, s[42:43]
	s_nop 0
	v_lshlrev_b64 v[16:17], 13, v[146:147]
	v_lshl_add_u64 v[16:17], s[14:15], 0, v[16:17]
	v_lshl_add_u64 v[16:17], v[144:145], 1, v[16:17]
	v_lshl_add_u64 v[16:17], v[16:17], 0, s[28:29]
	s_and_saveexec_b64 s[42:43], vcc
	s_cbranch_execz .LBB0_1779
	v_max_f32_e32 v12, 0, v12
	v_max_f32_e32 v13, 0, v13
	v_max_f32_e32 v14, 0, v14
	v_max_f32_e32 v15, 0, v15
	v_max_f32_e32 v8, 0, v8
	v_max_f32_e32 v9, 0, v9
	v_max_f32_e32 v10, 0, v10
	v_max_f32_e32 v11, 0, v11
	v_pk_mul_f32 v[12:13], v[12:13], v[12:13]
	v_pk_mul_f32 v[14:15], v[14:15], v[14:15]
	v_pk_mul_f32 v[8:9], v[8:9], v[8:9]
	v_pk_mul_f32 v[10:11], v[10:11], v[10:11]
	v_cvt_pk_bf16_f32 v8, v8, v9
	v_cvt_pk_bf16_f32 v9, v10, v11
	v_cvt_pk_bf16_f32 v10, v12, v13
	v_cvt_pk_bf16_f32 v11, v14, v15
	global_store_dwordx4 v[16:17], v[8:11], off
.LBB0_1779:
	s_or_b64 exec, exec, s[42:43]
	s_and_saveexec_b64 s[42:43], s[10:11]
	s_cbranch_execz .LBB0_1725
	v_max_f32_e32 v4, 0, v4
	v_max_f32_e32 v5, 0, v5
	v_max_f32_e32 v6, 0, v6
	v_max_f32_e32 v7, 0, v7
	v_max_f32_e32 v0, 0, v0
	v_max_f32_e32 v1, 0, v1
	v_max_f32_e32 v2, 0, v2
	v_max_f32_e32 v3, 0, v3
	v_pk_mul_f32 v[4:5], v[4:5], v[4:5]
	v_pk_mul_f32 v[6:7], v[6:7], v[6:7]
	v_pk_mul_f32 v[0:1], v[0:1], v[0:1]
	v_pk_mul_f32 v[2:3], v[2:3], v[2:3]
	v_cvt_pk_bf16_f32 v0, v0, v1
	v_cvt_pk_bf16_f32 v1, v2, v3
	v_cvt_pk_bf16_f32 v2, v4, v5
	v_cvt_pk_bf16_f32 v3, v6, v7
	global_store_dwordx4 v[16:17], v[0:3], off offset:256
	s_branch .LBB0_1725

.LBB0_1845:
	ds_read_b128 v[180:183], v162
	ds_read_b128 v[184:187], v163
	ds_read_b128 v[188:191], v164
	ds_read_b128 v[192:195], v165
	ds_read_b128 v[196:199], v166
	ds_read_b128 v[200:203], v167
	ds_read_b128 v[204:207], v168
	ds_read_b128 v[208:211], v169
	s_add_u32 s42, s36, s40
	s_addc_u32 s43, s37, s41
	s_add_u32 s42, s42, 0x100
	s_addc_u32 s43, s43, 0
	s_add_u32 s72, s69, s40
	s_addc_u32 s73, s70, s41
	s_cmpk_eq_i32 s40, 0x1f00
	s_cselect_b32 s45, s7, s43
	s_cselect_b32 s44, s21, s42
	s_cselect_b32 s43, s27, s73
	s_cselect_b32 s42, s29, s72
	s_mov_b32 m0, s65
	v_lshl_add_u64 v[244:245], v[156:157], 0, s[40:41]
	ds_read_b128 v[212:215], v160
	ds_read_b128 v[216:219], v160 offset:1024
	ds_read_b128 v[220:223], v160 offset:2048
	ds_read_b128 v[224:227], v160 offset:3072
	ds_read_b128 v[228:231], v160 offset:4096
	ds_read_b128 v[232:235], v160 offset:5120
	ds_read_b128 v[236:239], v160 offset:6144
	ds_read_b128 v[240:243], v160 offset:7168
	global_load_lds_dwordx4 v[244:245], off
	v_lshl_add_u64 v[244:245], v[154:155], 0, s[40:41]
	s_mov_b32 m0, s66
	s_nop 0
	global_load_lds_dwordx4 v[244:245], off
	v_lshl_add_u64 v[244:245], v[152:153], 0, s[40:41]
	s_mov_b32 m0, s67
	s_nop 0
	global_load_lds_dwordx4 v[244:245], off
	v_lshl_add_u64 v[244:245], v[150:151], 0, s[40:41]
	s_mov_b32 m0, s68
	s_nop 0
	global_load_lds_dwordx4 v[244:245], off
	s_waitcnt lgkmcnt(8)
	s_barrier
	s_waitcnt lgkmcnt(0)
	s_setprio 1
	s_waitcnt lgkmcnt(0)
	v_mfma_f32_16x16x32_bf16 v[124:127], v[180:183], v[212:215], v[124:127]
	v_mfma_f32_16x16x32_bf16 v[120:123], v[188:191], v[212:215], v[120:123]
	v_mfma_f32_16x16x32_bf16 v[116:119], v[180:183], v[220:223], v[116:119]
	v_mfma_f32_16x16x32_bf16 v[108:111], v[188:191], v[220:223], v[108:111]
	v_mfma_f32_16x16x32_bf16 v[100:103], v[180:183], v[228:231], v[100:103]
	v_mfma_f32_16x16x32_bf16 v[92:95], v[188:191], v[228:231], v[92:95]
	v_mfma_f32_16x16x32_bf16 v[84:87], v[180:183], v[236:239], v[84:87]
	v_mfma_f32_16x16x32_bf16 v[76:79], v[188:191], v[236:239], v[76:79]
	v_mfma_f32_16x16x32_bf16 v[124:127], v[184:187], v[216:219], v[124:127]
	v_mfma_f32_16x16x32_bf16 v[120:123], v[192:195], v[216:219], v[120:123]
	v_mfma_f32_16x16x32_bf16 v[116:119], v[184:187], v[224:227], v[116:119]
	v_mfma_f32_16x16x32_bf16 v[108:111], v[192:195], v[224:227], v[108:111]
	v_mfma_f32_16x16x32_bf16 v[100:103], v[184:187], v[232:235], v[100:103]
	v_mfma_f32_16x16x32_bf16 v[92:95], v[192:195], v[232:235], v[92:95]
	v_mfma_f32_16x16x32_bf16 v[84:87], v[184:187], v[240:243], v[84:87]
	v_mfma_f32_16x16x32_bf16 v[76:79], v[192:195], v[240:243], v[76:79]
	s_setprio 0
	s_setprio 1
	v_mfma_f32_16x16x32_bf16 v[112:115], v[196:199], v[212:215], v[112:115]
	v_mfma_f32_16x16x32_bf16 v[104:107], v[204:207], v[212:215], v[104:107]
	v_mfma_f32_16x16x32_bf16 v[96:99], v[196:199], v[220:223], v[96:99]
	v_mfma_f32_16x16x32_bf16 v[88:91], v[204:207], v[220:223], v[88:91]
	v_mfma_f32_16x16x32_bf16 v[80:83], v[196:199], v[228:231], v[80:83]
	v_mfma_f32_16x16x32_bf16 v[72:75], v[204:207], v[228:231], v[72:75]
	v_mfma_f32_16x16x32_bf16 v[68:71], v[196:199], v[236:239], v[68:71]
	v_mfma_f32_16x16x32_bf16 v[64:67], v[204:207], v[236:239], v[64:67]
	v_mfma_f32_16x16x32_bf16 v[112:115], v[200:203], v[216:219], v[112:115]
	v_mfma_f32_16x16x32_bf16 v[104:107], v[208:211], v[216:219], v[104:107]
	v_mfma_f32_16x16x32_bf16 v[96:99], v[200:203], v[224:227], v[96:99]
	v_mfma_f32_16x16x32_bf16 v[88:91], v[208:211], v[224:227], v[88:91]
	v_mfma_f32_16x16x32_bf16 v[80:83], v[200:203], v[232:235], v[80:83]
	v_mfma_f32_16x16x32_bf16 v[72:75], v[208:211], v[232:235], v[72:75]
	v_mfma_f32_16x16x32_bf16 v[68:71], v[200:203], v[240:243], v[68:71]
	v_mfma_f32_16x16x32_bf16 v[64:67], v[208:211], v[240:243], v[64:67]
	s_setprio 0
	s_barrier
	s_mov_b32 m0, s50
	v_lshl_add_u64 v[244:245], s[42:43], 0, v[136:137]
	s_add_u32 s72, s42, 0x100000
	ds_read_b128 v[212:215], v160 offset:16384
	ds_read_b128 v[216:219], v160 offset:17408
	ds_read_b128 v[220:223], v160 offset:18432
	ds_read_b128 v[224:227], v160 offset:19456
	ds_read_b128 v[228:231], v160 offset:20480
	ds_read_b128 v[232:235], v160 offset:21504
	ds_read_b128 v[236:239], v160 offset:22528
	ds_read_b128 v[240:243], v160 offset:23552
	global_load_lds_dwordx4 v[244:245], off
	v_lshl_add_u64 v[246:247], s[42:43], 0, v[138:139]
	s_mov_b32 m0, s51
	s_addc_u32 s73, s43, 0
	global_load_lds_dwordx4 v[246:247], off
	v_lshl_add_u64 v[248:249], s[72:73], 0, v[136:137]
	s_mov_b32 m0, s52
	s_nop 0
	global_load_lds_dwordx4 v[248:249], off
	v_lshl_add_u64 v[248:249], s[72:73], 0, v[138:139]
	s_mov_b32 m0, s53
	s_nop 0
	global_load_lds_dwordx4 v[248:249], off
	s_waitcnt vmcnt(4)
	s_waitcnt lgkmcnt(0)
	s_barrier
	s_setprio 1
	s_waitcnt lgkmcnt(0)
	v_mfma_f32_16x16x32_bf16 v[60:63], v[180:183], v[212:215], v[60:63]
	v_mfma_f32_16x16x32_bf16 v[56:59], v[188:191], v[212:215], v[56:59]
	v_mfma_f32_16x16x32_bf16 v[52:55], v[180:183], v[220:223], v[52:55]
	v_mfma_f32_16x16x32_bf16 v[44:47], v[188:191], v[220:223], v[44:47]
	v_mfma_f32_16x16x32_bf16 v[36:39], v[180:183], v[228:231], v[36:39]
	v_mfma_f32_16x16x32_bf16 v[28:31], v[188:191], v[228:231], v[28:31]
	v_mfma_f32_16x16x32_bf16 v[20:23], v[180:183], v[236:239], v[20:23]
	v_mfma_f32_16x16x32_bf16 v[12:15], v[188:191], v[236:239], v[12:15]
	v_mfma_f32_16x16x32_bf16 v[60:63], v[184:187], v[216:219], v[60:63]
	v_mfma_f32_16x16x32_bf16 v[56:59], v[192:195], v[216:219], v[56:59]
	v_mfma_f32_16x16x32_bf16 v[52:55], v[184:187], v[224:227], v[52:55]
	v_mfma_f32_16x16x32_bf16 v[44:47], v[192:195], v[224:227], v[44:47]
	v_mfma_f32_16x16x32_bf16 v[36:39], v[184:187], v[232:235], v[36:39]
	v_mfma_f32_16x16x32_bf16 v[28:31], v[192:195], v[232:235], v[28:31]
	v_mfma_f32_16x16x32_bf16 v[20:23], v[184:187], v[240:243], v[20:23]
	v_mfma_f32_16x16x32_bf16 v[12:15], v[192:195], v[240:243], v[12:15]
	s_setprio 0
	s_setprio 1
	v_mfma_f32_16x16x32_bf16 v[48:51], v[196:199], v[212:215], v[48:51]
	v_mfma_f32_16x16x32_bf16 v[40:43], v[204:207], v[212:215], v[40:43]
	v_mfma_f32_16x16x32_bf16 v[32:35], v[196:199], v[220:223], v[32:35]
	v_mfma_f32_16x16x32_bf16 v[24:27], v[204:207], v[220:223], v[24:27]
	v_mfma_f32_16x16x32_bf16 v[16:19], v[196:199], v[228:231], v[16:19]
	v_mfma_f32_16x16x32_bf16 v[8:11], v[204:207], v[228:231], v[8:11]
	v_mfma_f32_16x16x32_bf16 v[4:7], v[196:199], v[236:239], v[4:7]
	v_mfma_f32_16x16x32_bf16 v[0:3], v[204:207], v[236:239], v[0:3]
	v_mfma_f32_16x16x32_bf16 v[48:51], v[200:203], v[216:219], v[48:51]
	v_mfma_f32_16x16x32_bf16 v[40:43], v[208:211], v[216:219], v[40:43]
	v_mfma_f32_16x16x32_bf16 v[32:35], v[200:203], v[224:227], v[32:35]
	v_mfma_f32_16x16x32_bf16 v[24:27], v[208:211], v[224:227], v[24:27]
	v_mfma_f32_16x16x32_bf16 v[16:19], v[200:203], v[232:235], v[16:19]
	v_mfma_f32_16x16x32_bf16 v[8:11], v[208:211], v[232:235], v[8:11]
	v_mfma_f32_16x16x32_bf16 v[4:7], v[200:203], v[240:243], v[4:7]
	v_mfma_f32_16x16x32_bf16 v[0:3], v[208:211], v[240:243], v[0:3]
	s_setprio 0
	s_barrier
	ds_read_b128 v[180:183], v170
	ds_read_b128 v[184:187], v171
	ds_read_b128 v[188:191], v172
	ds_read_b128 v[192:195], v173
	ds_read_b128 v[196:199], v176
	ds_read_b128 v[200:203], v177
	ds_read_b128 v[204:207], v178
	ds_read_b128 v[208:211], v179
	s_mov_b32 m0, s49
	v_lshl_add_u64 v[248:249], s[44:45], 0, v[128:129]
	ds_read_b128 v[212:215], v160 offset:32768
	ds_read_b128 v[216:219], v160 offset:33792
	ds_read_b128 v[220:223], v160 offset:34816
	ds_read_b128 v[224:227], v160 offset:35840
	ds_read_b128 v[228:231], v160 offset:36864
	ds_read_b128 v[232:235], v160 offset:37888
	ds_read_b128 v[236:239], v160 offset:38912
	ds_read_b128 v[240:243], v160 offset:39936
	global_load_lds_dwordx4 v[248:249], off
	v_lshl_add_u64 v[248:249], s[44:45], 0, v[130:131]
	s_mov_b32 m0, s54
	s_nop 0
	global_load_lds_dwordx4 v[248:249], off
	v_lshl_add_u64 v[248:249], s[44:45], 0, v[132:133]
	s_mov_b32 m0, s55
	s_nop 0
	global_load_lds_dwordx4 v[248:249], off
	v_lshl_add_u64 v[248:249], s[44:45], 0, v[134:135]
	s_mov_b32 m0, s56
	s_nop 0
	global_load_lds_dwordx4 v[248:249], off
	s_waitcnt lgkmcnt(8)
	s_barrier
	s_waitcnt lgkmcnt(0)
	s_setprio 1
	s_waitcnt lgkmcnt(0)
	v_mfma_f32_16x16x32_bf16 v[124:127], v[180:183], v[212:215], v[124:127]
	v_mfma_f32_16x16x32_bf16 v[120:123], v[188:191], v[212:215], v[120:123]
	v_mfma_f32_16x16x32_bf16 v[116:119], v[180:183], v[220:223], v[116:119]
	v_mfma_f32_16x16x32_bf16 v[108:111], v[188:191], v[220:223], v[108:111]
	v_mfma_f32_16x16x32_bf16 v[100:103], v[180:183], v[228:231], v[100:103]
	v_mfma_f32_16x16x32_bf16 v[92:95], v[188:191], v[228:231], v[92:95]
	v_mfma_f32_16x16x32_bf16 v[84:87], v[180:183], v[236:239], v[84:87]
	v_mfma_f32_16x16x32_bf16 v[76:79], v[188:191], v[236:239], v[76:79]
	v_mfma_f32_16x16x32_bf16 v[124:127], v[184:187], v[216:219], v[124:127]
	v_mfma_f32_16x16x32_bf16 v[120:123], v[192:195], v[216:219], v[120:123]
	v_mfma_f32_16x16x32_bf16 v[116:119], v[184:187], v[224:227], v[116:119]
	v_mfma_f32_16x16x32_bf16 v[108:111], v[192:195], v[224:227], v[108:111]
	v_mfma_f32_16x16x32_bf16 v[100:103], v[184:187], v[232:235], v[100:103]
	v_mfma_f32_16x16x32_bf16 v[92:95], v[192:195], v[232:235], v[92:95]
	v_mfma_f32_16x16x32_bf16 v[84:87], v[184:187], v[240:243], v[84:87]
	v_mfma_f32_16x16x32_bf16 v[76:79], v[192:195], v[240:243], v[76:79]
	s_setprio 0
	s_setprio 1
	v_mfma_f32_16x16x32_bf16 v[112:115], v[196:199], v[212:215], v[112:115]
	v_mfma_f32_16x16x32_bf16 v[104:107], v[204:207], v[212:215], v[104:107]
	v_mfma_f32_16x16x32_bf16 v[96:99], v[196:199], v[220:223], v[96:99]
	v_mfma_f32_16x16x32_bf16 v[88:91], v[204:207], v[220:223], v[88:91]
	v_mfma_f32_16x16x32_bf16 v[80:83], v[196:199], v[228:231], v[80:83]
	v_mfma_f32_16x16x32_bf16 v[72:75], v[204:207], v[228:231], v[72:75]
	v_mfma_f32_16x16x32_bf16 v[68:71], v[196:199], v[236:239], v[68:71]
	v_mfma_f32_16x16x32_bf16 v[64:67], v[204:207], v[236:239], v[64:67]
	v_mfma_f32_16x16x32_bf16 v[112:115], v[200:203], v[216:219], v[112:115]
	v_mfma_f32_16x16x32_bf16 v[104:107], v[208:211], v[216:219], v[104:107]
	v_mfma_f32_16x16x32_bf16 v[96:99], v[200:203], v[224:227], v[96:99]
	v_mfma_f32_16x16x32_bf16 v[88:91], v[208:211], v[224:227], v[88:91]
	v_mfma_f32_16x16x32_bf16 v[80:83], v[200:203], v[232:235], v[80:83]
	v_mfma_f32_16x16x32_bf16 v[72:75], v[208:211], v[232:235], v[72:75]
	v_mfma_f32_16x16x32_bf16 v[68:71], v[200:203], v[240:243], v[68:71]
	v_mfma_f32_16x16x32_bf16 v[64:67], v[208:211], v[240:243], v[64:67]
	s_setprio 0
	s_barrier
	s_mov_b32 m0, s58
	v_lshl_add_u64 v[244:245], v[244:245], 0, s[14:15]
	s_add_u32 s42, s42, 0x100080
	ds_read_b128 v[212:215], v160 offset:49152
	ds_read_b128 v[216:219], v160 offset:50176
	ds_read_b128 v[220:223], v160 offset:51200
	ds_read_b128 v[224:227], v160 offset:52224
	ds_read_b128 v[228:231], v160 offset:53248
	ds_read_b128 v[232:235], v160 offset:54272
	ds_read_b128 v[236:239], v160 offset:55296
	ds_read_b128 v[240:243], v160 offset:56320
	global_load_lds_dwordx4 v[244:245], off
	v_lshl_add_u64 v[244:245], v[246:247], 0, s[14:15]
	s_mov_b32 m0, s59
	s_addc_u32 s43, s43, 0
	global_load_lds_dwordx4 v[244:245], off
	v_lshl_add_u64 v[244:245], s[42:43], 0, v[136:137]
	s_mov_b32 m0, s60
	s_nop 0
	global_load_lds_dwordx4 v[244:245], off
	v_lshl_add_u64 v[244:245], s[42:43], 0, v[138:139]
	s_mov_b32 m0, s61
	s_nop 0
	global_load_lds_dwordx4 v[244:245], off
	s_waitcnt vmcnt(4)
	s_waitcnt lgkmcnt(0)
	s_barrier
	s_setprio 1
	s_waitcnt lgkmcnt(0)
	v_mfma_f32_16x16x32_bf16 v[60:63], v[180:183], v[212:215], v[60:63]
	v_mfma_f32_16x16x32_bf16 v[56:59], v[188:191], v[212:215], v[56:59]
	v_mfma_f32_16x16x32_bf16 v[52:55], v[180:183], v[220:223], v[52:55]
	v_mfma_f32_16x16x32_bf16 v[44:47], v[188:191], v[220:223], v[44:47]
	v_mfma_f32_16x16x32_bf16 v[36:39], v[180:183], v[228:231], v[36:39]
	v_mfma_f32_16x16x32_bf16 v[28:31], v[188:191], v[228:231], v[28:31]
	v_mfma_f32_16x16x32_bf16 v[20:23], v[180:183], v[236:239], v[20:23]
	v_mfma_f32_16x16x32_bf16 v[12:15], v[188:191], v[236:239], v[12:15]
	v_mfma_f32_16x16x32_bf16 v[60:63], v[184:187], v[216:219], v[60:63]
	v_mfma_f32_16x16x32_bf16 v[56:59], v[192:195], v[216:219], v[56:59]
	v_mfma_f32_16x16x32_bf16 v[52:55], v[184:187], v[224:227], v[52:55]
	v_mfma_f32_16x16x32_bf16 v[44:47], v[192:195], v[224:227], v[44:47]
	v_mfma_f32_16x16x32_bf16 v[36:39], v[184:187], v[232:235], v[36:39]
	v_mfma_f32_16x16x32_bf16 v[28:31], v[192:195], v[232:235], v[28:31]
	v_mfma_f32_16x16x32_bf16 v[20:23], v[184:187], v[240:243], v[20:23]
	v_mfma_f32_16x16x32_bf16 v[12:15], v[192:195], v[240:243], v[12:15]
	s_setprio 0
	s_setprio 1
	v_mfma_f32_16x16x32_bf16 v[48:51], v[196:199], v[212:215], v[48:51]
	v_mfma_f32_16x16x32_bf16 v[40:43], v[204:207], v[212:215], v[40:43]
	v_mfma_f32_16x16x32_bf16 v[32:35], v[196:199], v[220:223], v[32:35]
	v_mfma_f32_16x16x32_bf16 v[24:27], v[204:207], v[220:223], v[24:27]
	v_mfma_f32_16x16x32_bf16 v[16:19], v[196:199], v[228:231], v[16:19]
	v_mfma_f32_16x16x32_bf16 v[8:11], v[204:207], v[228:231], v[8:11]
	v_mfma_f32_16x16x32_bf16 v[4:7], v[196:199], v[236:239], v[4:7]
	v_mfma_f32_16x16x32_bf16 v[0:3], v[204:207], v[236:239], v[0:3]
	v_mfma_f32_16x16x32_bf16 v[48:51], v[200:203], v[216:219], v[48:51]
	v_mfma_f32_16x16x32_bf16 v[40:43], v[208:211], v[216:219], v[40:43]
	v_mfma_f32_16x16x32_bf16 v[32:35], v[200:203], v[224:227], v[32:35]
	v_mfma_f32_16x16x32_bf16 v[24:27], v[208:211], v[224:227], v[24:27]
	v_mfma_f32_16x16x32_bf16 v[16:19], v[200:203], v[232:235], v[16:19]
	v_mfma_f32_16x16x32_bf16 v[8:11], v[208:211], v[232:235], v[8:11]
	v_mfma_f32_16x16x32_bf16 v[4:7], v[200:203], v[240:243], v[4:7]
	v_mfma_f32_16x16x32_bf16 v[0:3], v[208:211], v[240:243], v[0:3]
	s_setprio 0
	s_barrier
	s_add_i32 s71, s71, 2
	s_add_u32 s40, s40, 0x100
	s_addc_u32 s41, s41, 0
	s_cmp_gt_u32 s71, 61
	s_cbranch_scc0 .LBB0_1845
	v_lshl_add_u32 v152, s20, 8, v159
	v_ashrrev_i32_e32 v153, 31, v152
	v_lshl_or_b32 v150, s6, 8, v161
	v_lshlrev_b64 v[154:155], 11, v[152:153]
	v_ashrrev_i32_e32 v151, 31, v150
	v_lshl_add_u64 v[154:155], s[12:13], 0, v[154:155]
	v_lshl_add_u64 v[154:155], v[150:151], 1, v[154:155]
	v_cmp_gt_i32_e32 vcc, s57, v150
	s_and_saveexec_b64 s[6:7], vcc
	s_cbranch_execz .LBB0_1848
	v_cvt_pk_bf16_f32 v124, v124, v125
	v_cvt_pk_bf16_f32 v125, v126, v127
	v_cvt_pk_bf16_f32 v126, v120, v121
	v_cvt_pk_bf16_f32 v127, v122, v123
	global_store_dwordx4 v[154:155], v[124:127], off
.LBB0_1848:
	s_or_b64 exec, exec, s[6:7]
	v_or_b32_e32 v120, 0x80, v150
	v_cmp_gt_i32_e64 s[6:7], s57, v120
	s_and_saveexec_b64 s[20:21], s[6:7]
	s_cbranch_execz .LBB0_1850
	v_cvt_pk_bf16_f32 v112, v112, v113
	v_cvt_pk_bf16_f32 v113, v114, v115
	v_cvt_pk_bf16_f32 v114, v104, v105
	v_cvt_pk_bf16_f32 v115, v106, v107
	global_store_dwordx4 v[154:155], v[112:115], off offset:256
.LBB0_1850:
	s_or_b64 exec, exec, s[20:21]
	v_or_b32_e32 v104, 16, v152
	v_ashrrev_i32_e32 v105, 31, v104
	v_lshlrev_b64 v[104:105], 11, v[104:105]
	v_lshl_add_u64 v[104:105], s[12:13], 0, v[104:105]
	v_lshl_add_u64 v[104:105], v[150:151], 1, v[104:105]
	s_and_saveexec_b64 s[20:21], vcc
	s_cbranch_execz .LBB0_1852
	v_cvt_pk_bf16_f32 v106, v116, v117
	v_cvt_pk_bf16_f32 v107, v118, v119
	v_cvt_pk_bf16_f32 v108, v108, v109
	v_cvt_pk_bf16_f32 v109, v110, v111
	global_store_dwordx4 v[104:105], v[106:109], off
.LBB0_1852:
	s_or_b64 exec, exec, s[20:21]
	s_and_saveexec_b64 s[20:21], s[6:7]
	s_cbranch_execz .LBB0_1854
	v_cvt_pk_bf16_f32 v96, v96, v97
	v_cvt_pk_bf16_f32 v97, v98, v99
	v_cvt_pk_bf16_f32 v98, v88, v89
	v_cvt_pk_bf16_f32 v99, v90, v91
	global_store_dwordx4 v[104:105], v[96:99], off offset:256
.LBB0_1854:
	s_or_b64 exec, exec, s[20:21]
	v_or_b32_e32 v88, 32, v152
	v_ashrrev_i32_e32 v89, 31, v88
	v_lshlrev_b64 v[88:89], 11, v[88:89]
	v_lshl_add_u64 v[88:89], s[12:13], 0, v[88:89]
	v_lshl_add_u64 v[88:89], v[150:151], 1, v[88:89]
	s_and_saveexec_b64 s[20:21], vcc
	s_cbranch_execz .LBB0_1856
	v_cvt_pk_bf16_f32 v90, v100, v101
	v_cvt_pk_bf16_f32 v91, v102, v103
	v_cvt_pk_bf16_f32 v92, v92, v93
	v_cvt_pk_bf16_f32 v93, v94, v95
	global_store_dwordx4 v[88:89], v[90:93], off
.LBB0_1856:
	s_or_b64 exec, exec, s[20:21]
	s_and_saveexec_b64 s[20:21], s[6:7]
	s_cbranch_execz .LBB0_1858
	v_cvt_pk_bf16_f32 v80, v80, v81
	v_cvt_pk_bf16_f32 v81, v82, v83
	v_cvt_pk_bf16_f32 v82, v72, v73
	v_cvt_pk_bf16_f32 v83, v74, v75
	global_store_dwordx4 v[88:89], v[80:83], off offset:256
.LBB0_1858:
	s_or_b64 exec, exec, s[20:21]
	v_or_b32_e32 v72, 48, v152
	v_ashrrev_i32_e32 v73, 31, v72
	v_lshlrev_b64 v[72:73], 11, v[72:73]
	v_lshl_add_u64 v[72:73], s[12:13], 0, v[72:73]
	v_lshl_add_u64 v[72:73], v[150:151], 1, v[72:73]
	s_and_saveexec_b64 s[20:21], vcc
	s_cbranch_execz .LBB0_1860
	v_cvt_pk_bf16_f32 v74, v84, v85
	v_cvt_pk_bf16_f32 v75, v86, v87
	v_cvt_pk_bf16_f32 v76, v76, v77
	v_cvt_pk_bf16_f32 v77, v78, v79
	global_store_dwordx4 v[72:73], v[74:77], off
.LBB0_1860:
	s_or_b64 exec, exec, s[20:21]
	s_and_saveexec_b64 s[20:21], s[6:7]
	s_cbranch_execz .LBB0_1862
	v_cvt_pk_bf16_f32 v68, v68, v69
	v_cvt_pk_bf16_f32 v69, v70, v71
	v_cvt_pk_bf16_f32 v70, v64, v65
	v_cvt_pk_bf16_f32 v71, v66, v67
	global_store_dwordx4 v[72:73], v[68:71], off offset:256
.LBB0_1862:
	s_or_b64 exec, exec, s[20:21]
	v_lshlrev_b64 v[64:65], 11, v[152:153]
	v_lshl_add_u64 v[64:65], s[12:13], 0, v[64:65]
	v_lshl_add_u64 v[64:65], v[150:151], 1, v[64:65]
	v_lshl_add_u64 v[64:65], v[64:65], 0, s[16:17]
	s_and_saveexec_b64 s[20:21], vcc
	s_cbranch_execz .LBB0_1864
	v_cvt_pk_bf16_f32 v60, v60, v61
	v_cvt_pk_bf16_f32 v61, v62, v63
	v_cvt_pk_bf16_f32 v62, v56, v57
	v_cvt_pk_bf16_f32 v63, v58, v59
	global_store_dwordx4 v[64:65], v[60:63], off
.LBB0_1864:
	s_or_b64 exec, exec, s[20:21]
	s_and_saveexec_b64 s[20:21], s[6:7]
	s_cbranch_execz .LBB0_1866
	v_cvt_pk_bf16_f32 v48, v48, v49
	v_cvt_pk_bf16_f32 v49, v50, v51
	v_cvt_pk_bf16_f32 v50, v40, v41
	v_cvt_pk_bf16_f32 v51, v42, v43
	global_store_dwordx4 v[64:65], v[48:51], off offset:256
.LBB0_1866:
	s_or_b64 exec, exec, s[20:21]
	v_lshlrev_b64 v[40:41], 11, v[152:153]
	v_lshl_add_u64 v[40:41], s[12:13], 0, v[40:41]
	v_lshl_add_u64 v[40:41], v[150:151], 1, v[40:41]
	v_lshl_add_u64 v[40:41], v[40:41], 0, s[18:19]
	s_and_saveexec_b64 s[20:21], vcc
	s_cbranch_execz .LBB0_1868
	v_cvt_pk_bf16_f32 v42, v52, v53
	v_cvt_pk_bf16_f32 v43, v54, v55
	v_cvt_pk_bf16_f32 v44, v44, v45
	v_cvt_pk_bf16_f32 v45, v46, v47
	global_store_dwordx4 v[40:41], v[42:45], off
.LBB0_1868:
	s_or_b64 exec, exec, s[20:21]
	s_and_saveexec_b64 s[20:21], s[6:7]
	s_cbranch_execz .LBB0_1870
	v_cvt_pk_bf16_f32 v32, v32, v33
	v_cvt_pk_bf16_f32 v33, v34, v35
	v_cvt_pk_bf16_f32 v34, v24, v25
	v_cvt_pk_bf16_f32 v35, v26, v27
	global_store_dwordx4 v[40:41], v[32:35], off offset:256
.LBB0_1870:
	s_or_b64 exec, exec, s[20:21]
	v_lshlrev_b64 v[24:25], 11, v[152:153]
	v_lshl_add_u64 v[24:25], s[12:13], 0, v[24:25]
	v_lshl_add_u64 v[24:25], v[150:151], 1, v[24:25]
	v_lshl_add_u64 v[24:25], v[24:25], 0, s[22:23]
	s_and_saveexec_b64 s[20:21], vcc
	s_cbranch_execz .LBB0_1872
	v_cvt_pk_bf16_f32 v26, v36, v37
	v_cvt_pk_bf16_f32 v27, v38, v39
	v_cvt_pk_bf16_f32 v28, v28, v29
	v_cvt_pk_bf16_f32 v29, v30, v31
	global_store_dwordx4 v[24:25], v[26:29], off
.LBB0_1872:
	s_or_b64 exec, exec, s[20:21]
	s_and_saveexec_b64 s[20:21], s[6:7]
	s_cbranch_execz .LBB0_1874
	v_cvt_pk_bf16_f32 v16, v16, v17
	v_cvt_pk_bf16_f32 v17, v18, v19
	v_cvt_pk_bf16_f32 v18, v8, v9
	v_cvt_pk_bf16_f32 v19, v10, v11
	global_store_dwordx4 v[24:25], v[16:19], off offset:256
.LBB0_1874:
	s_or_b64 exec, exec, s[20:21]
	v_lshlrev_b64 v[8:9], 11, v[152:153]
	v_lshl_add_u64 v[8:9], s[12:13], 0, v[8:9]
	v_lshl_add_u64 v[8:9], v[150:151], 1, v[8:9]
	v_lshl_add_u64 v[8:9], v[8:9], 0, s[24:25]
	s_and_saveexec_b64 s[20:21], vcc
	s_cbranch_execz .LBB0_1876
	v_cvt_pk_bf16_f32 v10, v20, v21
	v_cvt_pk_bf16_f32 v11, v22, v23
	v_cvt_pk_bf16_f32 v12, v12, v13
	v_cvt_pk_bf16_f32 v13, v14, v15
	global_store_dwordx4 v[8:9], v[10:13], off
.LBB0_1876:
	s_or_b64 exec, exec, s[20:21]
	s_and_saveexec_b64 s[20:21], s[6:7]
	s_cbranch_execz .LBB0_1841
	v_cvt_pk_bf16_f32 v4, v4, v5
	v_cvt_pk_bf16_f32 v5, v6, v7
	v_cvt_pk_bf16_f32 v6, v0, v1
	v_cvt_pk_bf16_f32 v7, v2, v3
	global_store_dwordx4 v[8:9], v[4:7], off offset:256
	s_branch .LBB0_1841

.LBB0_2141:
	s_mulk_i32 s54, 0xc0
	v_add_u32_e32 v136, s54, v117
	v_lshl_or_b32 v112, s14, 8, v119
	v_mov_b64_e32 v[114:115], s[18:19]
	v_ashrrev_i32_e32 v113, 31, v112
	v_mad_i64_i32 v[114:115], s[10:11], v136, s71, v[114:115]
	v_lshl_add_u64 v[114:115], v[112:113], 1, v[114:115]
	v_cmp_gt_i32_e32 vcc, s72, v112
	s_and_saveexec_b64 s[10:11], vcc
	s_cbranch_execz .LBB0_2143
	v_cvt_pk_bf16_f32 v92, v92, v93
	v_cvt_pk_bf16_f32 v93, v94, v95
	v_cvt_pk_bf16_f32 v94, v88, v89
	v_cvt_pk_bf16_f32 v95, v90, v91
	global_store_dwordx4 v[114:115], v[92:95], off
.LBB0_2143:
	s_or_b64 exec, exec, s[10:11]
	v_or_b32_e32 v88, 0x80, v112
	v_cmp_gt_i32_e64 s[10:11], s72, v88
	s_and_saveexec_b64 s[14:15], s[10:11]
	s_cbranch_execz .LBB0_2145
	v_cvt_pk_bf16_f32 v84, v84, v85
	v_cvt_pk_bf16_f32 v85, v86, v87
	v_cvt_pk_bf16_f32 v86, v76, v77
	v_cvt_pk_bf16_f32 v87, v78, v79
	global_store_dwordx4 v[114:115], v[84:87], off offset:256
.LBB0_2145:
	s_or_b64 exec, exec, s[14:15]
	v_add_u32_e32 v78, 16, v136
	v_mov_b64_e32 v[76:77], s[18:19]
	v_mad_i64_i32 v[76:77], s[14:15], v78, s71, v[76:77]
	v_lshl_add_u64 v[76:77], v[112:113], 1, v[76:77]
	s_and_saveexec_b64 s[14:15], vcc
	s_cbranch_execz .LBB0_2147
	v_cvt_pk_bf16_f32 v78, v80, v81
	v_cvt_pk_bf16_f32 v79, v82, v83
	v_cvt_pk_bf16_f32 v80, v72, v73
	v_cvt_pk_bf16_f32 v81, v74, v75
	global_store_dwordx4 v[76:77], v[78:81], off
.LBB0_2147:
	s_or_b64 exec, exec, s[14:15]
	s_and_saveexec_b64 s[14:15], s[10:11]
	s_cbranch_execz .LBB0_2149
	v_cvt_pk_bf16_f32 v68, v68, v69
	v_cvt_pk_bf16_f32 v69, v70, v71
	v_cvt_pk_bf16_f32 v70, v60, v61
	v_cvt_pk_bf16_f32 v71, v62, v63
	global_store_dwordx4 v[76:77], v[68:71], off offset:256
.LBB0_2149:
	s_or_b64 exec, exec, s[14:15]
	v_add_u32_e32 v62, 32, v136
	v_mov_b64_e32 v[60:61], s[18:19]
	v_mad_i64_i32 v[60:61], s[14:15], v62, s71, v[60:61]
	v_lshl_add_u64 v[60:61], v[112:113], 1, v[60:61]
	s_and_saveexec_b64 s[14:15], vcc
	s_cbranch_execz .LBB0_2151
	v_cvt_pk_bf16_f32 v62, v64, v65
	v_cvt_pk_bf16_f32 v63, v66, v67
	v_cvt_pk_bf16_f32 v64, v56, v57
	v_cvt_pk_bf16_f32 v65, v58, v59
	global_store_dwordx4 v[60:61], v[62:65], off
.LBB0_2151:
	s_or_b64 exec, exec, s[14:15]
	s_and_saveexec_b64 s[14:15], s[10:11]
	s_cbranch_execz .LBB0_2153
	v_cvt_pk_bf16_f32 v52, v52, v53
	v_cvt_pk_bf16_f32 v53, v54, v55
	v_cvt_pk_bf16_f32 v54, v48, v49
	v_cvt_pk_bf16_f32 v55, v50, v51
	global_store_dwordx4 v[60:61], v[52:55], off offset:256
.LBB0_2153:
	s_or_b64 exec, exec, s[14:15]
	v_add_u32_e32 v50, 0x60, v136
	v_mov_b64_e32 v[48:49], s[18:19]
	v_mad_i64_i32 v[48:49], s[14:15], v50, s71, v[48:49]
	v_lshl_add_u64 v[48:49], v[112:113], 1, v[48:49]
	s_and_saveexec_b64 s[14:15], vcc
	s_cbranch_execz .LBB0_2155
	v_cvt_pk_bf16_f32 v44, v44, v45
	v_cvt_pk_bf16_f32 v45, v46, v47
	v_cvt_pk_bf16_f32 v46, v40, v41
	v_cvt_pk_bf16_f32 v47, v42, v43
	global_store_dwordx4 v[48:49], v[44:47], off
.LBB0_2155:
	s_or_b64 exec, exec, s[14:15]
	s_and_saveexec_b64 s[14:15], s[10:11]
	s_cbranch_execz .LBB0_2157
	v_cvt_pk_bf16_f32 v36, v36, v37
	v_cvt_pk_bf16_f32 v37, v38, v39
	v_cvt_pk_bf16_f32 v38, v28, v29
	v_cvt_pk_bf16_f32 v39, v30, v31
	global_store_dwordx4 v[48:49], v[36:39], off offset:256
.LBB0_2157:
	s_or_b64 exec, exec, s[14:15]
	v_add_u32_e32 v30, 0x70, v136
	v_mov_b64_e32 v[28:29], s[18:19]
	v_mad_i64_i32 v[28:29], s[14:15], v30, s71, v[28:29]
	v_lshl_add_u64 v[28:29], v[112:113], 1, v[28:29]
	s_and_saveexec_b64 s[14:15], vcc
	s_cbranch_execz .LBB0_2159
	v_cvt_pk_bf16_f32 v30, v32, v33
	v_cvt_pk_bf16_f32 v31, v34, v35
	v_cvt_pk_bf16_f32 v32, v24, v25
	v_cvt_pk_bf16_f32 v33, v26, v27
	global_store_dwordx4 v[28:29], v[30:33], off
.LBB0_2159:
	s_or_b64 exec, exec, s[14:15]
	s_and_saveexec_b64 s[14:15], s[10:11]
	s_cbranch_execz .LBB0_2161
	v_cvt_pk_bf16_f32 v20, v20, v21
	v_cvt_pk_bf16_f32 v21, v22, v23
	v_cvt_pk_bf16_f32 v22, v12, v13
	v_cvt_pk_bf16_f32 v23, v14, v15
	global_store_dwordx4 v[28:29], v[20:23], off offset:256
.LBB0_2161:
	s_or_b64 exec, exec, s[14:15]
	v_add_u32_e32 v14, 0x80, v136
	v_mov_b64_e32 v[12:13], s[18:19]
	v_mad_i64_i32 v[12:13], s[14:15], v14, s71, v[12:13]
	v_lshl_add_u64 v[12:13], v[112:113], 1, v[12:13]
	s_and_saveexec_b64 s[14:15], vcc
	s_cbranch_execz .LBB0_2163
	v_cvt_pk_bf16_f32 v14, v16, v17
	v_cvt_pk_bf16_f32 v15, v18, v19
	v_cvt_pk_bf16_f32 v16, v8, v9
	v_cvt_pk_bf16_f32 v17, v10, v11
	global_store_dwordx4 v[12:13], v[14:17], off
.LBB0_2163:
	s_or_b64 exec, exec, s[14:15]
	s_and_saveexec_b64 s[14:15], s[10:11]
	s_cbranch_execz .LBB0_2115
	v_cvt_pk_bf16_f32 v4, v4, v5
	v_cvt_pk_bf16_f32 v5, v6, v7
	v_cvt_pk_bf16_f32 v6, v0, v1
	v_cvt_pk_bf16_f32 v7, v2, v3
	global_store_dwordx4 v[12:13], v[4:7], off offset:256
	s_branch .LBB0_2115

.LBB0_3237:
	s_mulk_i32 s60, 0xc0
	v_add_u32_e32 v114, s60, v119
	v_ashrrev_i32_e32 v115, 31, v114
	v_lshl_or_b32 v112, s14, 8, v121
	v_lshlrev_b64 v[116:117], 11, v[114:115]
	v_ashrrev_i32_e32 v113, 31, v112
	v_lshl_add_u64 v[116:117], s[18:19], 0, v[116:117]
	v_lshl_add_u64 v[116:117], v[112:113], 1, v[116:117]
	v_cmp_gt_i32_e32 vcc, s72, v112
	s_and_saveexec_b64 s[10:11], vcc
	s_cbranch_execz .LBB0_3239
	v_cvt_pk_bf16_f32 v92, v92, v93
	v_cvt_pk_bf16_f32 v93, v94, v95
	v_cvt_pk_bf16_f32 v94, v88, v89
	v_cvt_pk_bf16_f32 v95, v90, v91
	global_store_dwordx4 v[116:117], v[92:95], off
.LBB0_3239:
	s_or_b64 exec, exec, s[10:11]
	v_or_b32_e32 v88, 0x80, v112
	v_cmp_gt_i32_e64 s[10:11], s72, v88
	s_and_saveexec_b64 s[14:15], s[10:11]
	s_cbranch_execz .LBB0_3241
	v_cvt_pk_bf16_f32 v84, v84, v85
	v_cvt_pk_bf16_f32 v85, v86, v87
	v_cvt_pk_bf16_f32 v86, v80, v81
	v_cvt_pk_bf16_f32 v87, v82, v83
	global_store_dwordx4 v[116:117], v[84:87], off offset:256
.LBB0_3241:
	s_or_b64 exec, exec, s[14:15]
	v_lshlrev_b64 v[80:81], 11, v[114:115]
	v_lshl_add_u64 v[80:81], s[18:19], 0, v[80:81]
	v_lshl_add_u64 v[80:81], v[112:113], 1, v[80:81]
	v_lshl_add_u64 v[80:81], v[80:81], 0, s[26:27]
	s_and_saveexec_b64 s[14:15], vcc
	s_cbranch_execz .LBB0_3243
	v_cvt_pk_bf16_f32 v76, v76, v77
	v_cvt_pk_bf16_f32 v77, v78, v79
	v_cvt_pk_bf16_f32 v78, v72, v73
	v_cvt_pk_bf16_f32 v79, v74, v75
	global_store_dwordx4 v[80:81], v[76:79], off
.LBB0_3243:
	s_or_b64 exec, exec, s[14:15]
	s_and_saveexec_b64 s[14:15], s[10:11]
	s_cbranch_execz .LBB0_3245
	v_cvt_pk_bf16_f32 v68, v68, v69
	v_cvt_pk_bf16_f32 v69, v70, v71
	v_cvt_pk_bf16_f32 v70, v64, v65
	v_cvt_pk_bf16_f32 v71, v66, v67
	global_store_dwordx4 v[80:81], v[68:71], off offset:256
.LBB0_3245:
	s_or_b64 exec, exec, s[14:15]
	v_lshlrev_b64 v[64:65], 11, v[114:115]
	v_lshl_add_u64 v[64:65], s[18:19], 0, v[64:65]
	v_lshl_add_u64 v[64:65], v[112:113], 1, v[64:65]
	v_lshl_add_u64 v[64:65], v[64:65], 0, s[28:29]
	s_and_saveexec_b64 s[14:15], vcc
	s_cbranch_execz .LBB0_3247
	v_cvt_pk_bf16_f32 v60, v60, v61
	v_cvt_pk_bf16_f32 v61, v62, v63
	v_cvt_pk_bf16_f32 v62, v56, v57
	v_cvt_pk_bf16_f32 v63, v58, v59
	global_store_dwordx4 v[64:65], v[60:63], off
.LBB0_3247:
	s_or_b64 exec, exec, s[14:15]
	s_and_saveexec_b64 s[14:15], s[10:11]
	s_cbranch_execz .LBB0_3249
	v_cvt_pk_bf16_f32 v52, v52, v53
	v_cvt_pk_bf16_f32 v53, v54, v55
	v_cvt_pk_bf16_f32 v54, v48, v49
	v_cvt_pk_bf16_f32 v55, v50, v51
	global_store_dwordx4 v[64:65], v[52:55], off offset:256
.LBB0_3249:
	s_or_b64 exec, exec, s[14:15]
	v_lshlrev_b64 v[48:49], 11, v[114:115]
	v_lshl_add_u64 v[48:49], s[18:19], 0, v[48:49]
	v_lshl_add_u64 v[48:49], v[112:113], 1, v[48:49]
	v_lshl_add_u64 v[48:49], v[48:49], 0, s[30:31]
	s_and_saveexec_b64 s[14:15], vcc
	s_cbranch_execz .LBB0_3251
	v_cvt_pk_bf16_f32 v44, v44, v45
	v_cvt_pk_bf16_f32 v45, v46, v47
	v_cvt_pk_bf16_f32 v46, v40, v41
	v_cvt_pk_bf16_f32 v47, v42, v43
	global_store_dwordx4 v[48:49], v[44:47], off
.LBB0_3251:
	s_or_b64 exec, exec, s[14:15]
	s_and_saveexec_b64 s[14:15], s[10:11]
	s_cbranch_execz .LBB0_3253
	v_cvt_pk_bf16_f32 v36, v36, v37
	v_cvt_pk_bf16_f32 v37, v38, v39
	v_cvt_pk_bf16_f32 v38, v32, v33
	v_cvt_pk_bf16_f32 v39, v34, v35
	global_store_dwordx4 v[48:49], v[36:39], off offset:256
.LBB0_3253:
	s_or_b64 exec, exec, s[14:15]
	v_lshlrev_b64 v[32:33], 11, v[114:115]
	v_lshl_add_u64 v[32:33], s[18:19], 0, v[32:33]
	v_lshl_add_u64 v[32:33], v[112:113], 1, v[32:33]
	v_lshl_add_u64 v[32:33], v[32:33], 0, s[34:35]
	s_and_saveexec_b64 s[14:15], vcc
	s_cbranch_execz .LBB0_3255
	v_cvt_pk_bf16_f32 v28, v28, v29
	v_cvt_pk_bf16_f32 v29, v30, v31
	v_cvt_pk_bf16_f32 v30, v24, v25
	v_cvt_pk_bf16_f32 v31, v26, v27
	global_store_dwordx4 v[32:33], v[28:31], off
.LBB0_3255:
	s_or_b64 exec, exec, s[14:15]
	s_and_saveexec_b64 s[14:15], s[10:11]
	s_cbranch_execz .LBB0_3257
	v_cvt_pk_bf16_f32 v20, v20, v21
	v_cvt_pk_bf16_f32 v21, v22, v23
	v_cvt_pk_bf16_f32 v22, v16, v17
	v_cvt_pk_bf16_f32 v23, v18, v19
	global_store_dwordx4 v[32:33], v[20:23], off offset:256
.LBB0_3257:
	s_or_b64 exec, exec, s[14:15]
	v_lshlrev_b64 v[16:17], 11, v[114:115]
	v_lshl_add_u64 v[16:17], s[18:19], 0, v[16:17]
	v_lshl_add_u64 v[16:17], v[112:113], 1, v[16:17]
	v_lshl_add_u64 v[16:17], v[16:17], 0, s[20:21]
	s_and_saveexec_b64 s[14:15], vcc
	s_cbranch_execz .LBB0_3259
	v_cvt_pk_bf16_f32 v12, v12, v13
	v_cvt_pk_bf16_f32 v13, v14, v15
	v_cvt_pk_bf16_f32 v14, v8, v9
	v_cvt_pk_bf16_f32 v15, v10, v11
	global_store_dwordx4 v[16:17], v[12:15], off
.LBB0_3259:
	s_or_b64 exec, exec, s[14:15]
	s_and_saveexec_b64 s[14:15], s[10:11]
	s_cbranch_execz .LBB0_3211
	v_cvt_pk_bf16_f32 v4, v4, v5
	v_cvt_pk_bf16_f32 v5, v6, v7
	v_cvt_pk_bf16_f32 v6, v0, v1
	v_cvt_pk_bf16_f32 v7, v2, v3
	global_store_dwordx4 v[16:17], v[4:7], off offset:256
	s_branch .LBB0_3211

.LBB0_3387:
	s_or_b64 exec, exec, s[10:11]
	s_nop 0
	v_or_b32_e32 v120, 0x80, v144
	v_cmp_gt_i32_e64 s[10:11], s81, v120
	s_and_saveexec_b64 s[42:43], s[10:11]
	s_cbranch_execz .LBB0_3389
	v_max_f32_e32 v116, 0, v116
	v_max_f32_e32 v117, 0, v117
	v_max_f32_e32 v118, 0, v118
	v_max_f32_e32 v119, 0, v119
	v_max_f32_e32 v112, 0, v112
	v_max_f32_e32 v113, 0, v113
	v_max_f32_e32 v114, 0, v114
	v_max_f32_e32 v115, 0, v115
	v_pk_mul_f32 v[116:117], v[116:117], v[116:117]
	v_pk_mul_f32 v[118:119], v[118:119], v[118:119]
	v_pk_mul_f32 v[112:113], v[112:113], v[112:113]
	v_pk_mul_f32 v[114:115], v[114:115], v[114:115]
	v_cvt_pk_bf16_f32 v112, v112, v113
	v_cvt_pk_bf16_f32 v113, v114, v115
	v_cvt_pk_bf16_f32 v114, v116, v117
	v_cvt_pk_bf16_f32 v115, v118, v119
	global_store_dwordx4 v[148:149], v[112:115], off offset:256

.LBB0_3483:
	ds_read_b128 v[142:145], v125
	ds_read_b128 v[146:149], v126
	ds_read_b128 v[150:153], v127
	ds_read_b128 v[154:157], v128
	ds_read_b128 v[158:161], v129
	ds_read_b128 v[162:165], v130
	ds_read_b128 v[166:169], v131
	ds_read_b128 v[170:173], v132
	s_add_u32 s34, s26, s6
	s_addc_u32 s35, s27, s7
	s_add_u32 s34, s34, 0x100
	s_addc_u32 s35, s35, 0
	s_add_u32 s65, s62, s6
	s_addc_u32 s66, s63, s7
	s_cmpk_eq_i32 s6, 0x1f00
	s_cselect_b32 s37, s29, s35
	s_cselect_b32 s36, s28, s34
	s_cselect_b32 s35, s13, s66
	s_cselect_b32 s34, s25, s65
	s_mov_b32 m0, s58
	v_lshl_add_u64 v[200:201], v[120:121], 0, s[6:7]
	ds_read_b128 v[176:179], v123
	ds_read_b128 v[180:183], v123 offset:1024
	ds_read_b128 v[184:187], v123 offset:2048
	ds_read_b128 v[188:191], v123 offset:3072
	ds_read_b128 v[192:195], v123 offset:4096
	ds_read_b128 v[196:199], v123 offset:5120
	global_load_lds_dwordx4 v[200:201], off
	v_lshl_add_u64 v[200:201], v[118:119], 0, s[6:7]
	s_mov_b32 m0, s59
	s_nop 0
	global_load_lds_dwordx4 v[200:201], off
	v_lshl_add_u64 v[200:201], v[116:117], 0, s[6:7]
	s_mov_b32 m0, s60
	s_nop 0
	global_load_lds_dwordx4 v[200:201], off
	s_waitcnt lgkmcnt(6)
	s_barrier
	s_waitcnt lgkmcnt(0)
	s_setprio 1
	s_waitcnt lgkmcnt(0)
	v_mfma_f32_16x16x32_bf16 v[92:95], v[142:145], v[176:179], v[92:95]
	v_mfma_f32_16x16x32_bf16 v[88:91], v[150:153], v[176:179], v[88:91]
	v_mfma_f32_16x16x32_bf16 v[76:79], v[142:145], v[184:187], v[76:79]
	v_mfma_f32_16x16x32_bf16 v[72:75], v[150:153], v[184:187], v[72:75]
	v_mfma_f32_16x16x32_bf16 v[60:63], v[142:145], v[192:195], v[60:63]
	v_mfma_f32_16x16x32_bf16 v[56:59], v[150:153], v[192:195], v[56:59]
	v_mfma_f32_16x16x32_bf16 v[92:95], v[146:149], v[180:183], v[92:95]
	v_mfma_f32_16x16x32_bf16 v[88:91], v[154:157], v[180:183], v[88:91]
	v_mfma_f32_16x16x32_bf16 v[76:79], v[146:149], v[188:191], v[76:79]
	v_mfma_f32_16x16x32_bf16 v[72:75], v[154:157], v[188:191], v[72:75]
	v_mfma_f32_16x16x32_bf16 v[60:63], v[146:149], v[196:199], v[60:63]
	v_mfma_f32_16x16x32_bf16 v[56:59], v[154:157], v[196:199], v[56:59]
	s_setprio 0
	s_setprio 1
	v_mfma_f32_16x16x32_bf16 v[84:87], v[158:161], v[176:179], v[84:87]
	v_mfma_f32_16x16x32_bf16 v[80:83], v[166:169], v[176:179], v[80:83]
	v_mfma_f32_16x16x32_bf16 v[68:71], v[158:161], v[184:187], v[68:71]
	v_mfma_f32_16x16x32_bf16 v[64:67], v[166:169], v[184:187], v[64:67]
	v_mfma_f32_16x16x32_bf16 v[52:55], v[158:161], v[192:195], v[52:55]
	v_mfma_f32_16x16x32_bf16 v[48:51], v[166:169], v[192:195], v[48:51]
	v_mfma_f32_16x16x32_bf16 v[84:87], v[162:165], v[180:183], v[84:87]
	v_mfma_f32_16x16x32_bf16 v[80:83], v[170:173], v[180:183], v[80:83]
	v_mfma_f32_16x16x32_bf16 v[68:71], v[162:165], v[188:191], v[68:71]
	v_mfma_f32_16x16x32_bf16 v[64:67], v[170:173], v[188:191], v[64:67]
	v_mfma_f32_16x16x32_bf16 v[52:55], v[162:165], v[196:199], v[52:55]
	v_mfma_f32_16x16x32_bf16 v[48:51], v[170:173], v[196:199], v[48:51]
	s_setprio 0
	s_barrier
	s_mov_b32 m0, s43
	v_lshl_add_u64 v[200:201], s[34:35], 0, v[102:103]
	s_add_u32 s66, s34, 0x100000
	ds_read_b128 v[176:179], v123 offset:12288
	ds_read_b128 v[180:183], v123 offset:13312
	ds_read_b128 v[184:187], v123 offset:14336
	ds_read_b128 v[188:191], v123 offset:15360
	ds_read_b128 v[192:195], v123 offset:16384
	ds_read_b128 v[196:199], v123 offset:17408
	global_load_lds_dwordx4 v[200:201], off
	v_lshl_add_u64 v[202:203], s[34:35], 0, v[104:105]
	s_mov_b32 m0, s44
	s_addc_u32 s67, s35, 0
	global_load_lds_dwordx4 v[202:203], off
	v_lshl_add_u64 v[204:205], s[66:67], 0, v[102:103]
	s_mov_b32 m0, s45
	s_nop 0
	global_load_lds_dwordx4 v[204:205], off
	v_lshl_add_u64 v[204:205], s[66:67], 0, v[104:105]
	s_mov_b32 m0, s46
	s_nop 0
	global_load_lds_dwordx4 v[204:205], off
	s_waitcnt vmcnt(4)
	s_waitcnt lgkmcnt(0)
	s_barrier
	s_setprio 1
	s_waitcnt lgkmcnt(0)
	v_mfma_f32_16x16x32_bf16 v[44:47], v[142:145], v[176:179], v[44:47]
	v_mfma_f32_16x16x32_bf16 v[40:43], v[150:153], v[176:179], v[40:43]
	v_mfma_f32_16x16x32_bf16 v[28:31], v[142:145], v[184:187], v[28:31]
	v_mfma_f32_16x16x32_bf16 v[24:27], v[150:153], v[184:187], v[24:27]
	v_mfma_f32_16x16x32_bf16 v[12:15], v[142:145], v[192:195], v[12:15]
	v_mfma_f32_16x16x32_bf16 v[8:11], v[150:153], v[192:195], v[8:11]
	v_mfma_f32_16x16x32_bf16 v[44:47], v[146:149], v[180:183], v[44:47]
	v_mfma_f32_16x16x32_bf16 v[40:43], v[154:157], v[180:183], v[40:43]
	v_mfma_f32_16x16x32_bf16 v[28:31], v[146:149], v[188:191], v[28:31]
	v_mfma_f32_16x16x32_bf16 v[24:27], v[154:157], v[188:191], v[24:27]
	v_mfma_f32_16x16x32_bf16 v[12:15], v[146:149], v[196:199], v[12:15]
	v_mfma_f32_16x16x32_bf16 v[8:11], v[154:157], v[196:199], v[8:11]
	s_setprio 0
	s_setprio 1
	v_mfma_f32_16x16x32_bf16 v[36:39], v[158:161], v[176:179], v[36:39]
	v_mfma_f32_16x16x32_bf16 v[32:35], v[166:169], v[176:179], v[32:35]
	v_mfma_f32_16x16x32_bf16 v[20:23], v[158:161], v[184:187], v[20:23]
	v_mfma_f32_16x16x32_bf16 v[16:19], v[166:169], v[184:187], v[16:19]
	v_mfma_f32_16x16x32_bf16 v[4:7], v[158:161], v[192:195], v[4:7]
	v_mfma_f32_16x16x32_bf16 v[0:3], v[166:169], v[192:195], v[0:3]
	v_mfma_f32_16x16x32_bf16 v[36:39], v[162:165], v[180:183], v[36:39]
	v_mfma_f32_16x16x32_bf16 v[32:35], v[170:173], v[180:183], v[32:35]
	v_mfma_f32_16x16x32_bf16 v[20:23], v[162:165], v[188:191], v[20:23]
	v_mfma_f32_16x16x32_bf16 v[16:19], v[170:173], v[188:191], v[16:19]
	v_mfma_f32_16x16x32_bf16 v[4:7], v[162:165], v[196:199], v[4:7]
	v_mfma_f32_16x16x32_bf16 v[0:3], v[170:173], v[196:199], v[0:3]
	s_setprio 0
	s_barrier
	ds_read_b128 v[142:145], v133
	ds_read_b128 v[146:149], v134
	ds_read_b128 v[150:153], v135
	ds_read_b128 v[154:157], v136
	ds_read_b128 v[158:161], v137
	ds_read_b128 v[162:165], v138
	ds_read_b128 v[166:169], v139
	ds_read_b128 v[170:173], v140
	s_mov_b32 m0, s42
	v_lshl_add_u64 v[204:205], s[36:37], 0, v[96:97]
	ds_read_b128 v[176:179], v123 offset:32768
	ds_read_b128 v[180:183], v123 offset:33792
	ds_read_b128 v[184:187], v123 offset:34816
	ds_read_b128 v[188:191], v123 offset:35840
	ds_read_b128 v[192:195], v123 offset:36864
	ds_read_b128 v[196:199], v123 offset:37888
	global_load_lds_dwordx4 v[204:205], off
	v_lshl_add_u64 v[204:205], s[36:37], 0, v[98:99]
	s_mov_b32 m0, s47
	s_nop 0
	global_load_lds_dwordx4 v[204:205], off
	v_lshl_add_u64 v[204:205], s[36:37], 0, v[100:101]
	s_mov_b32 m0, s48
	s_nop 0
	global_load_lds_dwordx4 v[204:205], off
	s_waitcnt lgkmcnt(6)
	s_barrier
	s_waitcnt lgkmcnt(0)
	s_setprio 1
	s_waitcnt lgkmcnt(0)
	v_mfma_f32_16x16x32_bf16 v[92:95], v[142:145], v[176:179], v[92:95]
	v_mfma_f32_16x16x32_bf16 v[88:91], v[150:153], v[176:179], v[88:91]
	v_mfma_f32_16x16x32_bf16 v[76:79], v[142:145], v[184:187], v[76:79]
	v_mfma_f32_16x16x32_bf16 v[72:75], v[150:153], v[184:187], v[72:75]
	v_mfma_f32_16x16x32_bf16 v[60:63], v[142:145], v[192:195], v[60:63]
	v_mfma_f32_16x16x32_bf16 v[56:59], v[150:153], v[192:195], v[56:59]
	v_mfma_f32_16x16x32_bf16 v[92:95], v[146:149], v[180:183], v[92:95]
	v_mfma_f32_16x16x32_bf16 v[88:91], v[154:157], v[180:183], v[88:91]
	v_mfma_f32_16x16x32_bf16 v[76:79], v[146:149], v[188:191], v[76:79]
	v_mfma_f32_16x16x32_bf16 v[72:75], v[154:157], v[188:191], v[72:75]
	v_mfma_f32_16x16x32_bf16 v[60:63], v[146:149], v[196:199], v[60:63]
	v_mfma_f32_16x16x32_bf16 v[56:59], v[154:157], v[196:199], v[56:59]
	s_setprio 0
	s_setprio 1
	v_mfma_f32_16x16x32_bf16 v[84:87], v[158:161], v[176:179], v[84:87]
	v_mfma_f32_16x16x32_bf16 v[80:83], v[166:169], v[176:179], v[80:83]
	v_mfma_f32_16x16x32_bf16 v[68:71], v[158:161], v[184:187], v[68:71]
	v_mfma_f32_16x16x32_bf16 v[64:67], v[166:169], v[184:187], v[64:67]
	v_mfma_f32_16x16x32_bf16 v[52:55], v[158:161], v[192:195], v[52:55]
	v_mfma_f32_16x16x32_bf16 v[48:51], v[166:169], v[192:195], v[48:51]
	v_mfma_f32_16x16x32_bf16 v[84:87], v[162:165], v[180:183], v[84:87]
	v_mfma_f32_16x16x32_bf16 v[80:83], v[170:173], v[180:183], v[80:83]
	v_mfma_f32_16x16x32_bf16 v[68:71], v[162:165], v[188:191], v[68:71]
	v_mfma_f32_16x16x32_bf16 v[64:67], v[170:173], v[188:191], v[64:67]
	v_mfma_f32_16x16x32_bf16 v[52:55], v[162:165], v[196:199], v[52:55]
	v_mfma_f32_16x16x32_bf16 v[48:51], v[170:173], v[196:199], v[48:51]
	s_setprio 0
	s_barrier
	s_mov_b32 m0, s50
	v_lshl_add_u64 v[200:201], v[200:201], 0, s[10:11]
	s_add_u32 s34, s34, 0x100080
	ds_read_b128 v[176:179], v123 offset:45056
	ds_read_b128 v[180:183], v123 offset:46080
	ds_read_b128 v[184:187], v123 offset:47104
	ds_read_b128 v[188:191], v123 offset:48128
	ds_read_b128 v[192:195], v123 offset:49152
	ds_read_b128 v[196:199], v123 offset:50176
	global_load_lds_dwordx4 v[200:201], off
	v_lshl_add_u64 v[200:201], v[202:203], 0, s[10:11]
	s_mov_b32 m0, s51
	s_addc_u32 s35, s35, 0
	global_load_lds_dwordx4 v[200:201], off
	v_lshl_add_u64 v[200:201], s[34:35], 0, v[102:103]
	s_mov_b32 m0, s52
	s_nop 0
	global_load_lds_dwordx4 v[200:201], off
	v_lshl_add_u64 v[200:201], s[34:35], 0, v[104:105]
	s_mov_b32 m0, s53
	s_nop 0
	global_load_lds_dwordx4 v[200:201], off
	s_waitcnt vmcnt(4)
	s_waitcnt lgkmcnt(0)
	s_barrier
	s_setprio 1
	s_waitcnt lgkmcnt(0)
	v_mfma_f32_16x16x32_bf16 v[44:47], v[142:145], v[176:179], v[44:47]
	v_mfma_f32_16x16x32_bf16 v[40:43], v[150:153], v[176:179], v[40:43]
	v_mfma_f32_16x16x32_bf16 v[28:31], v[142:145], v[184:187], v[28:31]
	v_mfma_f32_16x16x32_bf16 v[24:27], v[150:153], v[184:187], v[24:27]
	v_mfma_f32_16x16x32_bf16 v[12:15], v[142:145], v[192:195], v[12:15]
	v_mfma_f32_16x16x32_bf16 v[8:11], v[150:153], v[192:195], v[8:11]
	v_mfma_f32_16x16x32_bf16 v[44:47], v[146:149], v[180:183], v[44:47]
	v_mfma_f32_16x16x32_bf16 v[40:43], v[154:157], v[180:183], v[40:43]
	v_mfma_f32_16x16x32_bf16 v[28:31], v[146:149], v[188:191], v[28:31]
	v_mfma_f32_16x16x32_bf16 v[24:27], v[154:157], v[188:191], v[24:27]
	v_mfma_f32_16x16x32_bf16 v[12:15], v[146:149], v[196:199], v[12:15]
	v_mfma_f32_16x16x32_bf16 v[8:11], v[154:157], v[196:199], v[8:11]
	s_setprio 0
	s_setprio 1
	v_mfma_f32_16x16x32_bf16 v[36:39], v[158:161], v[176:179], v[36:39]
	v_mfma_f32_16x16x32_bf16 v[32:35], v[166:169], v[176:179], v[32:35]
	v_mfma_f32_16x16x32_bf16 v[20:23], v[158:161], v[184:187], v[20:23]
	v_mfma_f32_16x16x32_bf16 v[16:19], v[166:169], v[184:187], v[16:19]
	v_mfma_f32_16x16x32_bf16 v[4:7], v[158:161], v[192:195], v[4:7]
	v_mfma_f32_16x16x32_bf16 v[0:3], v[166:169], v[192:195], v[0:3]
	v_mfma_f32_16x16x32_bf16 v[36:39], v[162:165], v[180:183], v[36:39]
	v_mfma_f32_16x16x32_bf16 v[32:35], v[170:173], v[180:183], v[32:35]
	v_mfma_f32_16x16x32_bf16 v[20:23], v[162:165], v[188:191], v[20:23]
	v_mfma_f32_16x16x32_bf16 v[16:19], v[170:173], v[188:191], v[16:19]
	v_mfma_f32_16x16x32_bf16 v[4:7], v[162:165], v[196:199], v[4:7]
	v_mfma_f32_16x16x32_bf16 v[0:3], v[170:173], v[196:199], v[0:3]
	s_setprio 0
	s_barrier
	s_add_i32 s64, s64, 2
	s_add_u32 s6, s6, 0x100
	s_addc_u32 s7, s7, 0
	s_cmp_gt_u32 s64, 61
	s_cbranch_scc0 .LBB0_3483
	s_mul_i32 s6, s56, 0xc0
	v_add_u32_e32 v118, s6, v122
	v_ashrrev_i32_e32 v119, 31, v118
	v_lshl_or_b32 v116, s12, 8, v124
	v_lshlrev_b64 v[120:121], 11, v[118:119]
	v_ashrrev_i32_e32 v117, 31, v116
	v_lshl_add_u64 v[120:121], s[8:9], 0, v[120:121]
	v_lshl_add_u64 v[120:121], v[116:117], 1, v[120:121]
	v_cmp_gt_i32_e32 vcc, s49, v116
	s_and_saveexec_b64 s[6:7], vcc
	s_cbranch_execz .LBB0_3486
	v_cvt_pk_bf16_f32 v92, v92, v93
	v_cvt_pk_bf16_f32 v93, v94, v95
	v_cvt_pk_bf16_f32 v94, v88, v89
	v_cvt_pk_bf16_f32 v95, v90, v91
	global_store_dwordx4 v[120:121], v[92:95], off
.LBB0_3486:
	s_or_b64 exec, exec, s[6:7]
	v_or_b32_e32 v88, 0x80, v116
	v_cmp_gt_i32_e64 s[6:7], s49, v88
	s_and_saveexec_b64 s[12:13], s[6:7]
	s_cbranch_execz .LBB0_3488
	v_cvt_pk_bf16_f32 v84, v84, v85
	v_cvt_pk_bf16_f32 v85, v86, v87
	v_cvt_pk_bf16_f32 v86, v80, v81
	v_cvt_pk_bf16_f32 v87, v82, v83
	global_store_dwordx4 v[120:121], v[84:87], off offset:256
.LBB0_3488:
	s_or_b64 exec, exec, s[12:13]
	v_lshlrev_b64 v[80:81], 11, v[118:119]
	v_lshl_add_u64 v[80:81], s[8:9], 0, v[80:81]
	v_lshl_add_u64 v[80:81], v[116:117], 1, v[80:81]
	v_lshl_add_u64 v[80:81], v[80:81], 0, s[14:15]
	s_and_saveexec_b64 s[12:13], vcc
	s_cbranch_execz .LBB0_3490
	v_cvt_pk_bf16_f32 v76, v76, v77
	v_cvt_pk_bf16_f32 v77, v78, v79
	v_cvt_pk_bf16_f32 v78, v72, v73
	v_cvt_pk_bf16_f32 v79, v74, v75
	global_store_dwordx4 v[80:81], v[76:79], off
.LBB0_3490:
	s_or_b64 exec, exec, s[12:13]
	s_and_saveexec_b64 s[12:13], s[6:7]
	s_cbranch_execz .LBB0_3492
	v_cvt_pk_bf16_f32 v68, v68, v69
	v_cvt_pk_bf16_f32 v69, v70, v71
	v_cvt_pk_bf16_f32 v70, v64, v65
	v_cvt_pk_bf16_f32 v71, v66, v67
	global_store_dwordx4 v[80:81], v[68:71], off offset:256
.LBB0_3492:
	s_or_b64 exec, exec, s[12:13]
	v_lshlrev_b64 v[64:65], 11, v[118:119]
	v_lshl_add_u64 v[64:65], s[8:9], 0, v[64:65]
	v_lshl_add_u64 v[64:65], v[116:117], 1, v[64:65]
	v_lshl_add_u64 v[64:65], v[64:65], 0, s[16:17]
	s_and_saveexec_b64 s[12:13], vcc
	s_cbranch_execz .LBB0_3494
	v_cvt_pk_bf16_f32 v60, v60, v61
	v_cvt_pk_bf16_f32 v61, v62, v63
	v_cvt_pk_bf16_f32 v62, v56, v57
	v_cvt_pk_bf16_f32 v63, v58, v59
	global_store_dwordx4 v[64:65], v[60:63], off
.LBB0_3494:
	s_or_b64 exec, exec, s[12:13]
	s_and_saveexec_b64 s[12:13], s[6:7]
	s_cbranch_execz .LBB0_3496
	v_cvt_pk_bf16_f32 v52, v52, v53
	v_cvt_pk_bf16_f32 v53, v54, v55
	v_cvt_pk_bf16_f32 v54, v48, v49
	v_cvt_pk_bf16_f32 v55, v50, v51
	global_store_dwordx4 v[64:65], v[52:55], off offset:256
.LBB0_3496:
	s_or_b64 exec, exec, s[12:13]
	v_lshlrev_b64 v[48:49], 11, v[118:119]
	v_lshl_add_u64 v[48:49], s[8:9], 0, v[48:49]
	v_lshl_add_u64 v[48:49], v[116:117], 1, v[48:49]
	v_lshl_add_u64 v[48:49], v[48:49], 0, s[18:19]
	s_and_saveexec_b64 s[12:13], vcc
	s_cbranch_execz .LBB0_3498
	v_cvt_pk_bf16_f32 v44, v44, v45
	v_cvt_pk_bf16_f32 v45, v46, v47
	v_cvt_pk_bf16_f32 v46, v40, v41
	v_cvt_pk_bf16_f32 v47, v42, v43
	global_store_dwordx4 v[48:49], v[44:47], off
.LBB0_3498:
	s_or_b64 exec, exec, s[12:13]
	s_and_saveexec_b64 s[12:13], s[6:7]
	s_cbranch_execz .LBB0_3500
	v_cvt_pk_bf16_f32 v36, v36, v37
	v_cvt_pk_bf16_f32 v37, v38, v39
	v_cvt_pk_bf16_f32 v38, v32, v33
	v_cvt_pk_bf16_f32 v39, v34, v35
	global_store_dwordx4 v[48:49], v[36:39], off offset:256
.LBB0_3500:
	s_or_b64 exec, exec, s[12:13]
	v_lshlrev_b64 v[32:33], 11, v[118:119]
	v_lshl_add_u64 v[32:33], s[8:9], 0, v[32:33]
	v_lshl_add_u64 v[32:33], v[116:117], 1, v[32:33]
	v_lshl_add_u64 v[32:33], v[32:33], 0, s[20:21]
	s_and_saveexec_b64 s[12:13], vcc
	s_cbranch_execz .LBB0_3502
	v_cvt_pk_bf16_f32 v28, v28, v29
	v_cvt_pk_bf16_f32 v29, v30, v31
	v_cvt_pk_bf16_f32 v30, v24, v25
	v_cvt_pk_bf16_f32 v31, v26, v27
	global_store_dwordx4 v[32:33], v[28:31], off
.LBB0_3502:
	s_or_b64 exec, exec, s[12:13]
	s_and_saveexec_b64 s[12:13], s[6:7]
	s_cbranch_execz .LBB0_3504
	v_cvt_pk_bf16_f32 v20, v20, v21
	v_cvt_pk_bf16_f32 v21, v22, v23
	v_cvt_pk_bf16_f32 v22, v16, v17
	v_cvt_pk_bf16_f32 v23, v18, v19
	global_store_dwordx4 v[32:33], v[20:23], off offset:256
.LBB0_3504:
	s_or_b64 exec, exec, s[12:13]
	v_lshlrev_b64 v[16:17], 11, v[118:119]
	v_lshl_add_u64 v[16:17], s[8:9], 0, v[16:17]
	v_lshl_add_u64 v[16:17], v[116:117], 1, v[16:17]
	v_lshl_add_u64 v[16:17], v[16:17], 0, s[22:23]
	s_and_saveexec_b64 s[12:13], vcc
	s_cbranch_execz .LBB0_3506
	v_cvt_pk_bf16_f32 v12, v12, v13
	v_cvt_pk_bf16_f32 v13, v14, v15
	v_cvt_pk_bf16_f32 v14, v8, v9
	v_cvt_pk_bf16_f32 v15, v10, v11
	global_store_dwordx4 v[16:17], v[12:15], off
.LBB0_3506:
	s_or_b64 exec, exec, s[12:13]
	s_and_saveexec_b64 s[12:13], s[6:7]
	s_cbranch_execz .LBB0_3477
	v_cvt_pk_bf16_f32 v4, v4, v5
	v_cvt_pk_bf16_f32 v5, v6, v7
	v_cvt_pk_bf16_f32 v6, v0, v1
	v_cvt_pk_bf16_f32 v7, v2, v3
	global_store_dwordx4 v[16:17], v[4:7], off offset:256
	s_branch .LBB0_3477
